# GEMM K-loops: redundant post-barrier lgkmcnt(0) removed, pre-barrier vmcnt/lgkmcnt waits merged (on top of setprio flips removal)
# baseline (speedup 1.0000x reference)
; #define PG8_STAGE(bufoff, gbase, voff) do { _Pragma("unroll") for (int _i = 0; _i < 2; ++_i) \
;         __builtin_amdgcn_global_load_lds((const unsigned*)((const char*)(gbase) + (voff)[_i]), (PG8_LAS unsigned*)(lds + (bufoff) + ldsw + _i * 8192), 16, 0, 0); } while (0)
; #define PG8_LDA(dst, b, h) do { _Pragma("unroll") for (int m = 0; m < 4; ++m) _Pragma("unroll") for (int k = 0; k < 2; ++k) dst[m][k] = *(const PG8_LAS bf16x8*)(lds + PG8_SA(b, h) + aoff + m * 2048 + k * 1024); } while (0)
; #define PG8_LDB(dst, b, h) do { _Pragma("unroll") for (int n = 0; n < 2; ++n) _Pragma("unroll") for (int k = 0; k < 2; ++k) dst[n][k] = *(const PG8_LAS bf16x8*)(lds + PG8_SB(b, h) + boff + n * 2048 + k * 1024); } while (0)
; #define PG8_MMA(ai, bj, At, Bt) do { __builtin_amdgcn_s_setprio(1); _Pragma("unroll") for (int m = 0; m < 4; ++m) _Pragma("unroll") for (int n = 0; n < 2; ++n) _Pragma("unroll") for (int k = 0; k < 2; ++k) \
;         acc[ai][bj][m][n] = __builtin_amdgcn_mfma_f32_16x16x32_bf16(Bt[n][k], At[m][k], acc[ai][bj][m][n], 0, 0, 0); __builtin_amdgcn_s_setprio(0); } while (0)
; #define PG8_WAIT_V(n) asm volatile("s_waitcnt vmcnt(" #n ")" ::: "memory")
; #define PG8_WAIT_L(n) asm volatile("s_waitcnt lgkmcnt(" #n ")" ::: "memory")
; #define PG8_BAR __builtin_amdgcn_s_barrier()
; #define PG8_SCHED __builtin_amdgcn_sched_barrier(0)
; template <class Epi, class Sched, bool ALIGN_EPI = false, bool SP2 = false>
; __device__ __forceinline__ void gemm_phase(PG8_LAS unsigned char* lds, const Gemm g, const Sched& S, const Epi& E, const int tid) {
;     ...
;             const bool last = (t == nt - 2);
;             const char* a1 = cA + (size_t)(t + 1) * kstep;
;             const char* a2 = last ? nA : cA + (size_t)(t + 2) * kstep; const char* b2 = last ? nB : cB + (size_t)(t + 2) * kstep;
;             const char* a3 = a2 + kstep; const char* b3 = b2 + kstep;
;             if (last && has_next) S.a_ready(nxt);
;             if constexpr (SP2) {
;             PG8_LDB(B0, 0, 0); PG8_LDB(B1, 0, 1); PG8_SCHED; PG8_LDA(At, 0, 0); PG8_STAGE(PG8_SA(1, 1), a1 + hstep, voffA);
;             PG8_WAIT_V(8); PG8_WAIT_L(0); PG8_BAR; PG8_MMA(0, 0, At, B0); PG8_MMA(0, 1, At, B1); PG8_BAR; PG8_SCHED;
;             PG8_LDA(At, 0, 1); PG8_STAGE(PG8_SB(0, 0), b2, voffB); PG8_STAGE(PG8_SB(0, 1), b2 + hstep, voffB); PG8_STAGE(PG8_SA(0, 0), a2, voffA);
.LBB0_99:
	s_add_u32 s20, s18, 0xfffc0080
	s_addc_u32 s21, s19, -1
	s_add_i32 s50, 0, 0x10000
	s_cmp_eq_u32 s49, 12
	s_cselect_b32 s23, s13, s21
	s_cselect_b32 s22, s45, s20
	s_cselect_b32 s21, s11, s48
	s_cselect_b32 s20, s46, s47
	s_add_i32 s52, 0, 0x14000
	v_add_u32_e32 v132, s50, v153
	v_add_u32_e32 v148, s52, v153
	ds_read_b128 v[116:119], v132
	ds_read_b128 v[120:123], v132 offset:1024
	ds_read_b128 v[124:127], v132 offset:2048
	ds_read_b128 v[132:135], v132 offset:3072
	ds_read_b128 v[178:181], v148
	ds_read_b128 v[182:185], v148 offset:1024
	ds_read_b128 v[186:189], v148 offset:2048
	ds_read_b128 v[190:193], v148 offset:3072
	v_lshl_add_u64 v[148:149], s[18:19], 0, v[172:173]
	s_add_i32 m0, s36, 0xc000
	ds_read_b128 v[194:197], v176
	ds_read_b128 v[198:201], v176 offset:1024
	ds_read_b128 v[202:205], v176 offset:2048
	ds_read_b128 v[206:209], v176 offset:3072
	ds_read_b128 v[210:213], v176 offset:4096
	ds_read_b128 v[214:217], v176 offset:5120
	ds_read_b128 v[218:221], v176 offset:6144
	ds_read_b128 v[222:225], v176 offset:7168
	global_load_lds_dwordx4 v[148:149], off
	v_lshl_add_u64 v[148:149], s[18:19], 0, v[174:175]
	s_add_i32 m0, s36, 0xe000
	s_nop 0
	global_load_lds_dwordx4 v[148:149], off
	s_waitcnt vmcnt(8) lgkmcnt(0)
	s_barrier
	v_mfma_f32_16x16x32_bf16 v[144:147], v[116:119], v[194:197], v[144:147]
	v_mfma_f32_16x16x32_bf16 v[140:143], v[124:127], v[194:197], v[140:143]
	v_mfma_f32_16x16x32_bf16 v[112:115], v[116:119], v[202:205], v[112:115]
	v_mfma_f32_16x16x32_bf16 v[108:111], v[124:127], v[202:205], v[108:111]
	v_mfma_f32_16x16x32_bf16 v[96:99], v[116:119], v[210:213], v[96:99]
	v_mfma_f32_16x16x32_bf16 v[92:95], v[124:127], v[210:213], v[92:95]
	v_mfma_f32_16x16x32_bf16 v[80:83], v[116:119], v[218:221], v[80:83]
	v_mfma_f32_16x16x32_bf16 v[76:79], v[124:127], v[218:221], v[76:79]
	v_mfma_f32_16x16x32_bf16 v[144:147], v[120:123], v[198:201], v[144:147]
	v_mfma_f32_16x16x32_bf16 v[140:143], v[132:135], v[198:201], v[140:143]
	v_mfma_f32_16x16x32_bf16 v[112:115], v[120:123], v[206:209], v[112:115]
	v_mfma_f32_16x16x32_bf16 v[108:111], v[132:135], v[206:209], v[108:111]
	v_mfma_f32_16x16x32_bf16 v[96:99], v[120:123], v[214:217], v[96:99]
	v_mfma_f32_16x16x32_bf16 v[92:95], v[132:135], v[214:217], v[92:95]
	v_mfma_f32_16x16x32_bf16 v[80:83], v[120:123], v[222:225], v[80:83]
	v_mfma_f32_16x16x32_bf16 v[76:79], v[132:135], v[222:225], v[76:79]
	v_mfma_f32_16x16x32_bf16 v[136:139], v[178:181], v[194:197], v[136:139]
	v_mfma_f32_16x16x32_bf16 v[128:131], v[186:189], v[194:197], v[128:131]
	v_mfma_f32_16x16x32_bf16 v[104:107], v[178:181], v[202:205], v[104:107]
	v_mfma_f32_16x16x32_bf16 v[100:103], v[186:189], v[202:205], v[100:103]
	v_mfma_f32_16x16x32_bf16 v[88:91], v[178:181], v[210:213], v[88:91]
	v_mfma_f32_16x16x32_bf16 v[84:87], v[186:189], v[210:213], v[84:87]
	v_mfma_f32_16x16x32_bf16 v[72:75], v[178:181], v[218:221], v[72:75]
	v_mfma_f32_16x16x32_bf16 v[68:71], v[186:189], v[218:221], v[68:71]
	v_mfma_f32_16x16x32_bf16 v[136:139], v[182:185], v[198:201], v[136:139]
	v_mfma_f32_16x16x32_bf16 v[128:131], v[190:193], v[198:201], v[128:131]
	v_mfma_f32_16x16x32_bf16 v[104:107], v[182:185], v[206:209], v[104:107]
	v_mfma_f32_16x16x32_bf16 v[100:103], v[190:193], v[206:209], v[100:103]
	v_mfma_f32_16x16x32_bf16 v[88:91], v[182:185], v[214:217], v[88:91]
	v_mfma_f32_16x16x32_bf16 v[84:87], v[190:193], v[214:217], v[84:87]
	v_mfma_f32_16x16x32_bf16 v[72:75], v[182:185], v[222:225], v[72:75]
	v_mfma_f32_16x16x32_bf16 v[68:71], v[190:193], v[222:225], v[68:71]
	s_barrier
	s_add_i32 s50, s50, s26
	v_lshl_add_u64 v[148:149], s[20:21], 0, v[168:169]
	s_mov_b32 m0, s50
	ds_read_b128 v[194:197], v176 offset:16384
	ds_read_b128 v[198:201], v176 offset:17408
	ds_read_b128 v[202:205], v176 offset:18432
	ds_read_b128 v[206:209], v176 offset:19456
	ds_read_b128 v[210:213], v176 offset:20480
	ds_read_b128 v[214:217], v176 offset:21504
	ds_read_b128 v[218:221], v176 offset:22528
	ds_read_b128 v[222:225], v176 offset:23552
	global_load_lds_dwordx4 v[148:149], off
	s_add_i32 m0, s50, 0x2000
	s_add_u32 s50, s20, 0x40000
	v_lshl_add_u64 v[150:151], s[20:21], 0, v[0:1]
	s_addc_u32 s51, s21, 0
	s_add_i32 s52, s52, s26
	global_load_lds_dwordx4 v[150:151], off
	v_lshl_add_u64 v[226:227], s[50:51], 0, v[168:169]
	s_mov_b32 m0, s52
	v_lshl_add_u64 v[238:239], s[22:23], 0, v[166:167]
	global_load_lds_dwordx4 v[226:227], off
	v_lshl_add_u64 v[226:227], s[50:51], 0, v[0:1]
	s_add_i32 m0, s52, 0x2000
	s_nop 0
	global_load_lds_dwordx4 v[226:227], off
	v_lshl_add_u64 v[226:227], s[22:23], 0, v[170:171]
	s_mov_b32 m0, s36
	s_nop 0
	global_load_lds_dwordx4 v[226:227], off
	s_mov_b32 m0, s37
	s_nop 0
	global_load_lds_dwordx4 v[238:239], off
	s_waitcnt vmcnt(8) lgkmcnt(0)
	s_barrier
; #define PG8_STAGE(bufoff, gbase, voff) do { _Pragma("unroll") for (int _i = 0; _i < 2; ++_i) \
;         __builtin_amdgcn_global_load_lds((const unsigned*)((const char*)(gbase) + (voff)[_i]), (PG8_LAS unsigned*)(lds + (bufoff) + ldsw + _i * 8192), 16, 0, 0); } while (0)
; #define PG8_LDA(dst, b, h) do { _Pragma("unroll") for (int m = 0; m < 4; ++m) _Pragma("unroll") for (int k = 0; k < 2; ++k) dst[m][k] = *(const PG8_LAS bf16x8*)(lds + PG8_SA(b, h) + aoff + m * 2048 + k * 1024); } while (0)
; #define PG8_LDB(dst, b, h) do { _Pragma("unroll") for (int n = 0; n < 2; ++n) _Pragma("unroll") for (int k = 0; k < 2; ++k) dst[n][k] = *(const PG8_LAS bf16x8*)(lds + PG8_SB(b, h) + boff + n * 2048 + k * 1024); } while (0)
; #define PG8_MMA(ai, bj, At, Bt) do { __builtin_amdgcn_s_setprio(1); _Pragma("unroll") for (int m = 0; m < 4; ++m) _Pragma("unroll") for (int n = 0; n < 2; ++n) _Pragma("unroll") for (int k = 0; k < 2; ++k) \
;         acc[ai][bj][m][n] = __builtin_amdgcn_mfma_f32_16x16x32_bf16(Bt[n][k], At[m][k], acc[ai][bj][m][n], 0, 0, 0); __builtin_amdgcn_s_setprio(0); } while (0)
; #define PG8_WAIT_V(n) asm volatile("s_waitcnt vmcnt(" #n ")" ::: "memory")
; #define PG8_WAIT_L(n) asm volatile("s_waitcnt lgkmcnt(" #n ")" ::: "memory")
; #define PG8_BAR __builtin_amdgcn_s_barrier()
; #define PG8_SCHED __builtin_amdgcn_sched_barrier(0)
; template <class Epi, class Sched, bool ALIGN_EPI = false, bool SP2 = false>
; __device__ __forceinline__ void gemm_phase(PG8_LAS unsigned char* lds, const Gemm g, const Sched& S, const Epi& E, const int tid) {
;     ...
;             PG8_WAIT_V(8); PG8_WAIT_L(0); PG8_BAR; PG8_MMA(1, 0, At, B0); PG8_MMA(1, 1, At, B1); PG8_BAR; PG8_SCHED;
;             PG8_LDB(B0, 1, 0); PG8_LDB(B1, 1, 1); PG8_SCHED; PG8_LDA(At, 1, 0); PG8_STAGE(PG8_SA(0, 1), a2 + hstep, voffA);
;             PG8_WAIT_V(8); PG8_WAIT_L(0); PG8_BAR; PG8_MMA(0, 0, At, B0); PG8_MMA(0, 1, At, B1); PG8_BAR; PG8_SCHED;
	v_mfma_f32_16x16x32_bf16 v[64:67], v[116:119], v[194:197], v[64:67]
	v_mfma_f32_16x16x32_bf16 v[60:63], v[124:127], v[194:197], v[60:63]
	v_mfma_f32_16x16x32_bf16 v[56:59], v[116:119], v[202:205], v[56:59]
	v_mfma_f32_16x16x32_bf16 v[48:51], v[124:127], v[202:205], v[48:51]
	v_mfma_f32_16x16x32_bf16 v[40:43], v[116:119], v[210:213], v[40:43]
	v_mfma_f32_16x16x32_bf16 v[32:35], v[124:127], v[210:213], v[32:35]
	v_mfma_f32_16x16x32_bf16 v[24:27], v[116:119], v[218:221], v[24:27]
	v_mfma_f32_16x16x32_bf16 v[16:19], v[124:127], v[218:221], v[16:19]
	v_mfma_f32_16x16x32_bf16 v[64:67], v[120:123], v[198:201], v[64:67]
	v_mfma_f32_16x16x32_bf16 v[60:63], v[132:135], v[198:201], v[60:63]
	v_mfma_f32_16x16x32_bf16 v[56:59], v[120:123], v[206:209], v[56:59]
	v_mfma_f32_16x16x32_bf16 v[48:51], v[132:135], v[206:209], v[48:51]
	v_mfma_f32_16x16x32_bf16 v[40:43], v[120:123], v[214:217], v[40:43]
	v_mfma_f32_16x16x32_bf16 v[32:35], v[132:135], v[214:217], v[32:35]
	v_mfma_f32_16x16x32_bf16 v[24:27], v[120:123], v[222:225], v[24:27]
	v_mfma_f32_16x16x32_bf16 v[16:19], v[132:135], v[222:225], v[16:19]
	v_mfma_f32_16x16x32_bf16 v[52:55], v[178:181], v[194:197], v[52:55]
	v_mfma_f32_16x16x32_bf16 v[44:47], v[186:189], v[194:197], v[44:47]
	v_mfma_f32_16x16x32_bf16 v[36:39], v[178:181], v[202:205], v[36:39]
	v_mfma_f32_16x16x32_bf16 v[28:31], v[186:189], v[202:205], v[28:31]
	v_mfma_f32_16x16x32_bf16 v[20:23], v[178:181], v[210:213], v[20:23]
	v_mfma_f32_16x16x32_bf16 v[12:15], v[186:189], v[210:213], v[12:15]
	v_mfma_f32_16x16x32_bf16 v[8:11], v[178:181], v[218:221], v[8:11]
	v_mfma_f32_16x16x32_bf16 v[4:7], v[186:189], v[218:221], v[4:7]
	v_mfma_f32_16x16x32_bf16 v[52:55], v[182:185], v[198:201], v[52:55]
	v_mfma_f32_16x16x32_bf16 v[44:47], v[190:193], v[198:201], v[44:47]
	v_mfma_f32_16x16x32_bf16 v[36:39], v[182:185], v[206:209], v[36:39]
	v_mfma_f32_16x16x32_bf16 v[28:31], v[190:193], v[206:209], v[28:31]
	v_mfma_f32_16x16x32_bf16 v[20:23], v[182:185], v[214:217], v[20:23]
	v_mfma_f32_16x16x32_bf16 v[12:15], v[190:193], v[214:217], v[12:15]
	v_mfma_f32_16x16x32_bf16 v[8:11], v[182:185], v[222:225], v[8:11]
	v_mfma_f32_16x16x32_bf16 v[4:7], v[190:193], v[222:225], v[4:7]
	s_barrier
	s_add_i32 s50, 0, 0x18000
	s_add_i32 s51, 0, 0x1c000
	v_add_u32_e32 v132, s50, v153
	v_add_u32_e32 v177, s51, v153
	ds_read_b128 v[116:119], v132
	ds_read_b128 v[120:123], v132 offset:1024
	ds_read_b128 v[124:127], v132 offset:2048
	ds_read_b128 v[132:135], v132 offset:3072
	ds_read_b128 v[178:181], v177
	ds_read_b128 v[182:185], v177 offset:1024
	ds_read_b128 v[186:189], v177 offset:2048
	ds_read_b128 v[190:193], v177 offset:3072
	s_add_u32 s22, s22, 0x40000
	s_addc_u32 s23, s23, 0
	s_mov_b32 m0, s38
	v_lshl_add_u64 v[240:241], s[22:23], 0, v[170:171]
	ds_read_b128 v[194:197], v176 offset:32768
	ds_read_b128 v[198:201], v176 offset:33792
	ds_read_b128 v[202:205], v176 offset:34816
	ds_read_b128 v[206:209], v176 offset:35840
	ds_read_b128 v[210:213], v176 offset:36864
	ds_read_b128 v[214:217], v176 offset:37888
	ds_read_b128 v[218:221], v176 offset:38912
	ds_read_b128 v[222:225], v176 offset:39936
	global_load_lds_dwordx4 v[240:241], off
	v_lshl_add_u64 v[240:241], s[22:23], 0, v[166:167]
	s_mov_b32 m0, s39
	s_nop 0
	global_load_lds_dwordx4 v[240:241], off
	s_waitcnt vmcnt(8) lgkmcnt(0)
	s_barrier
	v_mfma_f32_16x16x32_bf16 v[144:147], v[116:119], v[194:197], v[144:147]
	v_mfma_f32_16x16x32_bf16 v[140:143], v[124:127], v[194:197], v[140:143]
	v_mfma_f32_16x16x32_bf16 v[112:115], v[116:119], v[202:205], v[112:115]
	v_mfma_f32_16x16x32_bf16 v[108:111], v[124:127], v[202:205], v[108:111]
	v_mfma_f32_16x16x32_bf16 v[96:99], v[116:119], v[210:213], v[96:99]
	v_mfma_f32_16x16x32_bf16 v[92:95], v[124:127], v[210:213], v[92:95]
	v_mfma_f32_16x16x32_bf16 v[80:83], v[116:119], v[218:221], v[80:83]
	v_mfma_f32_16x16x32_bf16 v[76:79], v[124:127], v[218:221], v[76:79]
	v_mfma_f32_16x16x32_bf16 v[144:147], v[120:123], v[198:201], v[144:147]
	v_mfma_f32_16x16x32_bf16 v[140:143], v[132:135], v[198:201], v[140:143]
	v_mfma_f32_16x16x32_bf16 v[112:115], v[120:123], v[206:209], v[112:115]
	v_mfma_f32_16x16x32_bf16 v[108:111], v[132:135], v[206:209], v[108:111]
	v_mfma_f32_16x16x32_bf16 v[96:99], v[120:123], v[214:217], v[96:99]
	v_mfma_f32_16x16x32_bf16 v[92:95], v[132:135], v[214:217], v[92:95]
	v_mfma_f32_16x16x32_bf16 v[80:83], v[120:123], v[222:225], v[80:83]
	v_mfma_f32_16x16x32_bf16 v[76:79], v[132:135], v[222:225], v[76:79]
	v_mfma_f32_16x16x32_bf16 v[136:139], v[178:181], v[194:197], v[136:139]
	v_mfma_f32_16x16x32_bf16 v[128:131], v[186:189], v[194:197], v[128:131]
	v_mfma_f32_16x16x32_bf16 v[104:107], v[178:181], v[202:205], v[104:107]
	v_mfma_f32_16x16x32_bf16 v[100:103], v[186:189], v[202:205], v[100:103]
	v_mfma_f32_16x16x32_bf16 v[88:91], v[178:181], v[210:213], v[88:91]
	v_mfma_f32_16x16x32_bf16 v[84:87], v[186:189], v[210:213], v[84:87]
	v_mfma_f32_16x16x32_bf16 v[72:75], v[178:181], v[218:221], v[72:75]
	v_mfma_f32_16x16x32_bf16 v[68:71], v[186:189], v[218:221], v[68:71]
	v_mfma_f32_16x16x32_bf16 v[136:139], v[182:185], v[198:201], v[136:139]
	v_mfma_f32_16x16x32_bf16 v[128:131], v[190:193], v[198:201], v[128:131]
	v_mfma_f32_16x16x32_bf16 v[104:107], v[182:185], v[206:209], v[104:107]
	v_mfma_f32_16x16x32_bf16 v[100:103], v[190:193], v[206:209], v[100:103]
	v_mfma_f32_16x16x32_bf16 v[88:91], v[182:185], v[214:217], v[88:91]
	v_mfma_f32_16x16x32_bf16 v[84:87], v[190:193], v[214:217], v[84:87]
	v_mfma_f32_16x16x32_bf16 v[72:75], v[182:185], v[222:225], v[72:75]
	v_mfma_f32_16x16x32_bf16 v[68:71], v[190:193], v[222:225], v[68:71]
	s_barrier
; #define PG8_STAGE(bufoff, gbase, voff) do { _Pragma("unroll") for (int _i = 0; _i < 2; ++_i) \
;         __builtin_amdgcn_global_load_lds((const unsigned*)((const char*)(gbase) + (voff)[_i]), (PG8_LAS unsigned*)(lds + (bufoff) + ldsw + _i * 8192), 16, 0, 0); } while (0)
; #define PG8_LDA(dst, b, h) do { _Pragma("unroll") for (int m = 0; m < 4; ++m) _Pragma("unroll") for (int k = 0; k < 2; ++k) dst[m][k] = *(const PG8_LAS bf16x8*)(lds + PG8_SA(b, h) + aoff + m * 2048 + k * 1024); } while (0)
; #define PG8_MMA(ai, bj, At, Bt) do { __builtin_amdgcn_s_setprio(1); _Pragma("unroll") for (int m = 0; m < 4; ++m) _Pragma("unroll") for (int n = 0; n < 2; ++n) _Pragma("unroll") for (int k = 0; k < 2; ++k) \
;         acc[ai][bj][m][n] = __builtin_amdgcn_mfma_f32_16x16x32_bf16(Bt[n][k], At[m][k], acc[ai][bj][m][n], 0, 0, 0); __builtin_amdgcn_s_setprio(0); } while (0)
; #define PG8_WAIT_V(n) asm volatile("s_waitcnt vmcnt(" #n ")" ::: "memory")
; #define PG8_WAIT_L(n) asm volatile("s_waitcnt lgkmcnt(" #n ")" ::: "memory")
; #define PG8_BAR __builtin_amdgcn_s_barrier()
; #define PG8_SCHED __builtin_amdgcn_sched_barrier(0)
; template <class Epi, class Sched, bool ALIGN_EPI = false, bool SP2 = false>
; __device__ __forceinline__ void gemm_phase(PG8_LAS unsigned char* lds, const Gemm g, const Sched& S, const Epi& E, const int tid) {
;     ...
;             PG8_LDA(At, 1, 1); PG8_STAGE(PG8_SB(1, 0), b3, voffB); PG8_STAGE(PG8_SB(1, 1), b3 + hstep, voffB); PG8_STAGE(PG8_SA(1, 0), a3, voffA);
;             PG8_WAIT_V(8); PG8_WAIT_L(0); PG8_BAR; PG8_MMA(1, 0, At, B0); PG8_MMA(1, 1, At, B1); PG8_BAR; PG8_SCHED;
;     ...
;         if constexpr (ALIGN_EPI) { if (wr == 0) PG8_BAR; }
	s_add_i32 s22, s50, s26
	v_lshl_add_u64 v[148:149], v[148:149], 0, s[0:1]
	s_mov_b32 m0, s22
	ds_read_b128 v[194:197], v176 offset:49152
	ds_read_b128 v[198:201], v176 offset:50176
	ds_read_b128 v[202:205], v176 offset:51200
	ds_read_b128 v[206:209], v176 offset:52224
	ds_read_b128 v[210:213], v176 offset:53248
	ds_read_b128 v[214:217], v176 offset:54272
	ds_read_b128 v[218:221], v176 offset:55296
	ds_read_b128 v[222:225], v176 offset:56320
	global_load_lds_dwordx4 v[148:149], off
	s_add_i32 m0, s22, 0x2000
	s_add_u32 s20, s20, 0x40080
	v_lshl_add_u64 v[148:149], v[150:151], 0, s[0:1]
	s_addc_u32 s21, s21, 0
	s_add_i32 s22, s51, s26
	global_load_lds_dwordx4 v[148:149], off
	v_lshl_add_u64 v[148:149], s[20:21], 0, v[168:169]
	s_mov_b32 m0, s22
	s_nop 0
	global_load_lds_dwordx4 v[148:149], off
	v_lshl_add_u64 v[148:149], s[20:21], 0, v[0:1]
	s_add_i32 m0, s22, 0x2000
	s_nop 0
	global_load_lds_dwordx4 v[148:149], off
	v_lshl_add_u64 v[148:149], v[226:227], 0, s[0:1]
	s_mov_b32 m0, s40
	s_nop 0
	global_load_lds_dwordx4 v[148:149], off
	v_lshl_add_u64 v[148:149], v[238:239], 0, s[0:1]
	s_mov_b32 m0, s41
	s_nop 0
	global_load_lds_dwordx4 v[148:149], off
	s_waitcnt vmcnt(8) lgkmcnt(0)
	s_barrier
	v_mfma_f32_16x16x32_bf16 v[64:67], v[116:119], v[194:197], v[64:67]
	v_mfma_f32_16x16x32_bf16 v[60:63], v[124:127], v[194:197], v[60:63]
	v_mfma_f32_16x16x32_bf16 v[56:59], v[116:119], v[202:205], v[56:59]
	v_mfma_f32_16x16x32_bf16 v[48:51], v[124:127], v[202:205], v[48:51]
	v_mfma_f32_16x16x32_bf16 v[40:43], v[116:119], v[210:213], v[40:43]
	v_mfma_f32_16x16x32_bf16 v[32:35], v[124:127], v[210:213], v[32:35]
	v_mfma_f32_16x16x32_bf16 v[24:27], v[116:119], v[218:221], v[24:27]
	v_mfma_f32_16x16x32_bf16 v[16:19], v[124:127], v[218:221], v[16:19]
	v_mfma_f32_16x16x32_bf16 v[64:67], v[120:123], v[198:201], v[64:67]
	v_mfma_f32_16x16x32_bf16 v[60:63], v[132:135], v[198:201], v[60:63]
	v_mfma_f32_16x16x32_bf16 v[56:59], v[120:123], v[206:209], v[56:59]
	v_mfma_f32_16x16x32_bf16 v[48:51], v[132:135], v[206:209], v[48:51]
	v_mfma_f32_16x16x32_bf16 v[40:43], v[120:123], v[214:217], v[40:43]
	v_mfma_f32_16x16x32_bf16 v[32:35], v[132:135], v[214:217], v[32:35]
	v_mfma_f32_16x16x32_bf16 v[24:27], v[120:123], v[222:225], v[24:27]
	v_mfma_f32_16x16x32_bf16 v[16:19], v[132:135], v[222:225], v[16:19]
	v_mfma_f32_16x16x32_bf16 v[52:55], v[178:181], v[194:197], v[52:55]
	v_mfma_f32_16x16x32_bf16 v[44:47], v[186:189], v[194:197], v[44:47]
	v_mfma_f32_16x16x32_bf16 v[36:39], v[178:181], v[202:205], v[36:39]
	v_mfma_f32_16x16x32_bf16 v[28:31], v[186:189], v[202:205], v[28:31]
	v_mfma_f32_16x16x32_bf16 v[20:23], v[178:181], v[210:213], v[20:23]
	v_mfma_f32_16x16x32_bf16 v[12:15], v[186:189], v[210:213], v[12:15]
	v_mfma_f32_16x16x32_bf16 v[8:11], v[178:181], v[218:221], v[8:11]
	v_mfma_f32_16x16x32_bf16 v[4:7], v[186:189], v[218:221], v[4:7]
	v_mfma_f32_16x16x32_bf16 v[52:55], v[182:185], v[198:201], v[52:55]
	v_mfma_f32_16x16x32_bf16 v[44:47], v[190:193], v[198:201], v[44:47]
	v_mfma_f32_16x16x32_bf16 v[36:39], v[182:185], v[206:209], v[36:39]
	v_mfma_f32_16x16x32_bf16 v[28:31], v[190:193], v[206:209], v[28:31]
	v_mfma_f32_16x16x32_bf16 v[20:23], v[182:185], v[214:217], v[20:23]
	v_mfma_f32_16x16x32_bf16 v[12:15], v[190:193], v[214:217], v[12:15]
	v_mfma_f32_16x16x32_bf16 v[8:11], v[182:185], v[222:225], v[8:11]
	v_mfma_f32_16x16x32_bf16 v[4:7], v[190:193], v[222:225], v[4:7]
	s_barrier
	s_add_i32 s49, s49, 2
	s_add_u32 s18, s18, 0x100
	s_addc_u32 s19, s19, 0
	s_add_u32 s47, s47, 0x100
	s_addc_u32 s48, s48, 0
	s_cmp_gt_u32 s49, 13
	s_cbranch_scc0 .LBB0_99
	s_and_b64 vcc, exec, s[8:9]
	s_cbranch_vccz .LBB0_102
	s_barrier

; #define PG8_STAGE(bufoff, gbase, voff) do { _Pragma("unroll") for (int _i = 0; _i < 2; ++_i) \
;         __builtin_amdgcn_global_load_lds((const unsigned*)((const char*)(gbase) + (voff)[_i]), (PG8_LAS unsigned*)(lds + (bufoff) + ldsw + _i * 8192), 16, 0, 0); } while (0)
; #define PG8_LDA(dst, b, h) do { _Pragma("unroll") for (int m = 0; m < 4; ++m) _Pragma("unroll") for (int k = 0; k < 2; ++k) dst[m][k] = *(const PG8_LAS bf16x8*)(lds + PG8_SA(b, h) + aoff + m * 2048 + k * 1024); } while (0)
; #define PG8_LDB(dst, b, h) do { _Pragma("unroll") for (int n = 0; n < 2; ++n) _Pragma("unroll") for (int k = 0; k < 2; ++k) dst[n][k] = *(const PG8_LAS bf16x8*)(lds + PG8_SB(b, h) + boff + n * 2048 + k * 1024); } while (0)
; #define PG8_MMA(ai, bj, At, Bt) do { __builtin_amdgcn_s_setprio(1); _Pragma("unroll") for (int m = 0; m < 4; ++m) _Pragma("unroll") for (int n = 0; n < 2; ++n) _Pragma("unroll") for (int k = 0; k < 2; ++k) \
;         acc[ai][bj][m][n] = __builtin_amdgcn_mfma_f32_16x16x32_bf16(Bt[n][k], At[m][k], acc[ai][bj][m][n], 0, 0, 0); __builtin_amdgcn_s_setprio(0); } while (0)
; #define PG8_WAIT_V(n) asm volatile("s_waitcnt vmcnt(" #n ")" ::: "memory")
; #define PG8_WAIT_L(n) asm volatile("s_waitcnt lgkmcnt(" #n ")" ::: "memory")
; #define PG8_BAR __builtin_amdgcn_s_barrier()
; #define PG8_SCHED __builtin_amdgcn_sched_barrier(0)
; template <class Epi, class Sched, bool ALIGN_EPI = false, bool SP2 = false>
; __device__ __forceinline__ void gemm_phase(PG8_LAS unsigned char* lds, const Gemm g, const Sched& S, const Epi& E, const int tid) {
;     ...
;             const bool last = (t == nt - 2);
;             const char* a1 = cA + (size_t)(t + 1) * kstep;
;             const char* a2 = last ? nA : cA + (size_t)(t + 2) * kstep; const char* b2 = last ? nB : cB + (size_t)(t + 2) * kstep;
;             const char* a3 = a2 + kstep; const char* b3 = b2 + kstep;
;             if (last && has_next) S.a_ready(nxt);
;             if constexpr (SP2) {
;             PG8_LDB(B0, 0, 0); PG8_LDB(B1, 0, 1); PG8_SCHED; PG8_LDA(At, 0, 0); PG8_STAGE(PG8_SA(1, 1), a1 + hstep, voffA);
;             PG8_WAIT_V(8); PG8_WAIT_L(0); PG8_BAR; PG8_MMA(0, 0, At, B0); PG8_MMA(0, 1, At, B1); PG8_BAR; PG8_SCHED;
;             PG8_LDA(At, 0, 1); PG8_STAGE(PG8_SB(0, 0), b2, voffB); PG8_STAGE(PG8_SB(0, 1), b2 + hstep, voffB); PG8_STAGE(PG8_SA(0, 0), a2, voffA);
.LBB0_293:
	s_add_u32 s26, s2, 0xfffc0080
	s_addc_u32 s27, s3, -1
	s_add_i32 s55, 0, 0x10000
	s_cmp_eq_u32 s54, 12
	s_cselect_b32 s37, s17, s27
	s_cselect_b32 s36, s23, s26
	v_add_u32_e32 v146, s55, v165
	s_cselect_b32 s27, s15, s53
	s_cselect_b32 s26, s51, s52
	s_add_i32 s58, 0, 0x14000
	ds_read_b128 v[166:169], v146
	ds_read_b128 v[172:175], v146 offset:1024
	ds_read_b128 v[176:179], v146 offset:2048
	ds_read_b128 v[180:183], v146 offset:3072
	v_add_u32_e32 v146, s58, v165
	ds_read_b128 v[184:187], v146
	ds_read_b128 v[188:191], v146 offset:1024
	ds_read_b128 v[192:195], v146 offset:2048
	ds_read_b128 v[196:199], v146 offset:3072
	v_lshl_add_u64 v[146:147], s[2:3], 0, v[142:143]
	s_add_i32 m0, s25, 0xc000
	ds_read_b128 v[200:203], v171
	ds_read_b128 v[204:207], v171 offset:1024
	ds_read_b128 v[208:211], v171 offset:2048
	ds_read_b128 v[212:215], v171 offset:3072
	ds_read_b128 v[216:219], v171 offset:4096
	ds_read_b128 v[220:223], v171 offset:5120
	ds_read_b128 v[224:227], v171 offset:6144
	ds_read_b128 v[238:241], v171 offset:7168
	global_load_lds_dwordx4 v[146:147], off
	v_lshl_add_u64 v[146:147], s[2:3], 0, v[144:145]
	s_add_i32 m0, s25, 0xe000
	s_nop 0
	global_load_lds_dwordx4 v[146:147], off
	s_waitcnt vmcnt(8) lgkmcnt(0)
	s_barrier
	v_mfma_f32_16x16x32_bf16 v[72:75], v[166:169], v[200:203], v[72:75]
	v_mfma_f32_16x16x32_bf16 v[68:71], v[176:179], v[200:203], v[68:71]
	v_mfma_f32_16x16x32_bf16 v[64:67], v[166:169], v[208:211], v[64:67]
	v_mfma_f32_16x16x32_bf16 v[60:63], v[176:179], v[208:211], v[60:63]
	v_mfma_f32_16x16x32_bf16 v[56:59], v[166:169], v[216:219], v[56:59]
	v_mfma_f32_16x16x32_bf16 v[52:55], v[176:179], v[216:219], v[52:55]
	v_mfma_f32_16x16x32_bf16 v[48:51], v[166:169], v[224:227], v[48:51]
	v_mfma_f32_16x16x32_bf16 v[44:47], v[176:179], v[224:227], v[44:47]
	v_mfma_f32_16x16x32_bf16 v[72:75], v[172:175], v[204:207], v[72:75]
	v_mfma_f32_16x16x32_bf16 v[68:71], v[180:183], v[204:207], v[68:71]
	v_mfma_f32_16x16x32_bf16 v[64:67], v[172:175], v[212:215], v[64:67]
	v_mfma_f32_16x16x32_bf16 v[60:63], v[180:183], v[212:215], v[60:63]
	v_mfma_f32_16x16x32_bf16 v[56:59], v[172:175], v[220:223], v[56:59]
	v_mfma_f32_16x16x32_bf16 v[52:55], v[180:183], v[220:223], v[52:55]
	v_mfma_f32_16x16x32_bf16 v[48:51], v[172:175], v[238:241], v[48:51]
	v_mfma_f32_16x16x32_bf16 v[44:47], v[180:183], v[238:241], v[44:47]
	v_mfma_f32_16x16x32_bf16 v[128:131], v[184:187], v[200:203], v[128:131]
	v_mfma_f32_16x16x32_bf16 v[124:127], v[192:195], v[200:203], v[124:127]
	v_mfma_f32_16x16x32_bf16 v[120:123], v[184:187], v[208:211], v[120:123]
	v_mfma_f32_16x16x32_bf16 v[116:119], v[192:195], v[208:211], v[116:119]
	v_mfma_f32_16x16x32_bf16 v[112:115], v[184:187], v[216:219], v[112:115]
	v_mfma_f32_16x16x32_bf16 v[108:111], v[192:195], v[216:219], v[108:111]
	v_mfma_f32_16x16x32_bf16 v[104:107], v[184:187], v[224:227], v[104:107]
	v_mfma_f32_16x16x32_bf16 v[100:103], v[192:195], v[224:227], v[100:103]
	v_mfma_f32_16x16x32_bf16 v[128:131], v[188:191], v[204:207], v[128:131]
	v_mfma_f32_16x16x32_bf16 v[124:127], v[196:199], v[204:207], v[124:127]
	v_mfma_f32_16x16x32_bf16 v[120:123], v[188:191], v[212:215], v[120:123]
	v_mfma_f32_16x16x32_bf16 v[116:119], v[196:199], v[212:215], v[116:119]
	v_mfma_f32_16x16x32_bf16 v[112:115], v[188:191], v[220:223], v[112:115]
	v_mfma_f32_16x16x32_bf16 v[108:111], v[196:199], v[220:223], v[108:111]
	v_mfma_f32_16x16x32_bf16 v[104:107], v[188:191], v[238:241], v[104:107]
	v_mfma_f32_16x16x32_bf16 v[100:103], v[196:199], v[238:241], v[100:103]
	s_barrier
	s_add_i32 s55, s55, s43
	v_lshl_add_u64 v[146:147], s[26:27], 0, v[132:133]
	s_mov_b32 m0, s55
	ds_read_b128 v[200:203], v171 offset:16384
	ds_read_b128 v[204:207], v171 offset:17408
	ds_read_b128 v[208:211], v171 offset:18432
	ds_read_b128 v[212:215], v171 offset:19456
	ds_read_b128 v[216:219], v171 offset:20480
	ds_read_b128 v[220:223], v171 offset:21504
	ds_read_b128 v[224:227], v171 offset:22528
	ds_read_b128 v[238:241], v171 offset:23552
	global_load_lds_dwordx4 v[146:147], off
	s_add_i32 m0, s55, 0x2000
	s_add_u32 s56, s26, 0x40000
	v_lshl_add_u64 v[148:149], s[26:27], 0, v[136:137]
	s_addc_u32 s57, s27, 0
	s_add_i32 s55, s58, s43
	global_load_lds_dwordx4 v[148:149], off
	v_lshl_add_u64 v[150:151], s[56:57], 0, v[132:133]
	s_mov_b32 m0, s55
	v_lshl_add_u64 v[242:243], s[36:37], 0, v[134:135]
	global_load_lds_dwordx4 v[150:151], off
	v_lshl_add_u64 v[150:151], s[56:57], 0, v[136:137]
	s_add_i32 m0, s55, 0x2000
	s_nop 0
	global_load_lds_dwordx4 v[150:151], off
	v_lshl_add_u64 v[150:151], s[36:37], 0, v[0:1]
	s_mov_b32 m0, s25
	s_nop 0
	global_load_lds_dwordx4 v[150:151], off
	s_mov_b32 m0, s44
	s_nop 0
	global_load_lds_dwordx4 v[242:243], off
	s_waitcnt vmcnt(8) lgkmcnt(0)
	s_barrier
; #define PG8_STAGE(bufoff, gbase, voff) do { _Pragma("unroll") for (int _i = 0; _i < 2; ++_i) \
;         __builtin_amdgcn_global_load_lds((const unsigned*)((const char*)(gbase) + (voff)[_i]), (PG8_LAS unsigned*)(lds + (bufoff) + ldsw + _i * 8192), 16, 0, 0); } while (0)
; #define PG8_LDA(dst, b, h) do { _Pragma("unroll") for (int m = 0; m < 4; ++m) _Pragma("unroll") for (int k = 0; k < 2; ++k) dst[m][k] = *(const PG8_LAS bf16x8*)(lds + PG8_SA(b, h) + aoff + m * 2048 + k * 1024); } while (0)
; #define PG8_LDB(dst, b, h) do { _Pragma("unroll") for (int n = 0; n < 2; ++n) _Pragma("unroll") for (int k = 0; k < 2; ++k) dst[n][k] = *(const PG8_LAS bf16x8*)(lds + PG8_SB(b, h) + boff + n * 2048 + k * 1024); } while (0)
; #define PG8_MMA(ai, bj, At, Bt) do { __builtin_amdgcn_s_setprio(1); _Pragma("unroll") for (int m = 0; m < 4; ++m) _Pragma("unroll") for (int n = 0; n < 2; ++n) _Pragma("unroll") for (int k = 0; k < 2; ++k) \
;         acc[ai][bj][m][n] = __builtin_amdgcn_mfma_f32_16x16x32_bf16(Bt[n][k], At[m][k], acc[ai][bj][m][n], 0, 0, 0); __builtin_amdgcn_s_setprio(0); } while (0)
; #define PG8_WAIT_V(n) asm volatile("s_waitcnt vmcnt(" #n ")" ::: "memory")
; #define PG8_WAIT_L(n) asm volatile("s_waitcnt lgkmcnt(" #n ")" ::: "memory")
; #define PG8_BAR __builtin_amdgcn_s_barrier()
; #define PG8_SCHED __builtin_amdgcn_sched_barrier(0)
; template <class Epi, class Sched, bool ALIGN_EPI = false, bool SP2 = false>
; __device__ __forceinline__ void gemm_phase(PG8_LAS unsigned char* lds, const Gemm g, const Sched& S, const Epi& E, const int tid) {
;     ...
;             PG8_WAIT_V(8); PG8_WAIT_L(0); PG8_BAR; PG8_MMA(1, 0, At, B0); PG8_MMA(1, 1, At, B1); PG8_BAR; PG8_SCHED;
;             PG8_LDB(B0, 1, 0); PG8_LDB(B1, 1, 1); PG8_SCHED; PG8_LDA(At, 1, 0); PG8_STAGE(PG8_SA(0, 1), a2 + hstep, voffA);
;             PG8_WAIT_V(8); PG8_WAIT_L(0); PG8_BAR; PG8_MMA(0, 0, At, B0); PG8_MMA(0, 1, At, B1); PG8_BAR; PG8_SCHED;
	v_mfma_f32_16x16x32_bf16 v[40:43], v[166:169], v[200:203], v[40:43]
	v_mfma_f32_16x16x32_bf16 v[36:39], v[176:179], v[200:203], v[36:39]
	v_mfma_f32_16x16x32_bf16 v[32:35], v[166:169], v[208:211], v[32:35]
	v_mfma_f32_16x16x32_bf16 v[28:31], v[176:179], v[208:211], v[28:31]
	v_mfma_f32_16x16x32_bf16 v[24:27], v[166:169], v[216:219], v[24:27]
	v_mfma_f32_16x16x32_bf16 v[20:23], v[176:179], v[216:219], v[20:23]
	v_mfma_f32_16x16x32_bf16 v[8:11], v[166:169], v[224:227], v[8:11]
	v_mfma_f32_16x16x32_bf16 v[4:7], v[176:179], v[224:227], v[4:7]
	v_mfma_f32_16x16x32_bf16 v[40:43], v[172:175], v[204:207], v[40:43]
	v_mfma_f32_16x16x32_bf16 v[36:39], v[180:183], v[204:207], v[36:39]
	v_mfma_f32_16x16x32_bf16 v[32:35], v[172:175], v[212:215], v[32:35]
	v_mfma_f32_16x16x32_bf16 v[28:31], v[180:183], v[212:215], v[28:31]
	v_mfma_f32_16x16x32_bf16 v[24:27], v[172:175], v[220:223], v[24:27]
	v_mfma_f32_16x16x32_bf16 v[20:23], v[180:183], v[220:223], v[20:23]
	v_mfma_f32_16x16x32_bf16 v[8:11], v[172:175], v[238:241], v[8:11]
	v_mfma_f32_16x16x32_bf16 v[4:7], v[180:183], v[238:241], v[4:7]
	v_mfma_f32_16x16x32_bf16 v[96:99], v[184:187], v[200:203], v[96:99]
	v_mfma_f32_16x16x32_bf16 v[92:95], v[192:195], v[200:203], v[92:95]
	v_mfma_f32_16x16x32_bf16 v[88:91], v[184:187], v[208:211], v[88:91]
	v_mfma_f32_16x16x32_bf16 v[84:87], v[192:195], v[208:211], v[84:87]
	v_mfma_f32_16x16x32_bf16 v[80:83], v[184:187], v[216:219], v[80:83]
	v_mfma_f32_16x16x32_bf16 v[76:79], v[192:195], v[216:219], v[76:79]
	v_mfma_f32_16x16x32_bf16 v[16:19], v[184:187], v[224:227], v[16:19]
	v_mfma_f32_16x16x32_bf16 v[12:15], v[192:195], v[224:227], v[12:15]
	v_mfma_f32_16x16x32_bf16 v[96:99], v[188:191], v[204:207], v[96:99]
	v_mfma_f32_16x16x32_bf16 v[92:95], v[196:199], v[204:207], v[92:95]
	v_mfma_f32_16x16x32_bf16 v[88:91], v[188:191], v[212:215], v[88:91]
	v_mfma_f32_16x16x32_bf16 v[84:87], v[196:199], v[212:215], v[84:87]
	v_mfma_f32_16x16x32_bf16 v[80:83], v[188:191], v[220:223], v[80:83]
	v_mfma_f32_16x16x32_bf16 v[76:79], v[196:199], v[220:223], v[76:79]
	v_mfma_f32_16x16x32_bf16 v[16:19], v[188:191], v[238:241], v[16:19]
	v_mfma_f32_16x16x32_bf16 v[12:15], v[196:199], v[238:241], v[12:15]
	s_barrier
	s_add_i32 s55, 0, 0x18000
	v_add_u32_e32 v153, s55, v165
	s_add_i32 s56, 0, 0x1c000
	ds_read_b128 v[166:169], v153
	ds_read_b128 v[172:175], v153 offset:1024
	ds_read_b128 v[176:179], v153 offset:2048
	ds_read_b128 v[180:183], v153 offset:3072
	v_add_u32_e32 v153, s56, v165
	ds_read_b128 v[184:187], v153
	ds_read_b128 v[188:191], v153 offset:1024
	ds_read_b128 v[192:195], v153 offset:2048
	ds_read_b128 v[196:199], v153 offset:3072
	s_add_u32 s36, s36, 0x40000
	s_addc_u32 s37, s37, 0
	s_mov_b32 m0, s45
	v_lshl_add_u64 v[244:245], s[36:37], 0, v[0:1]
	ds_read_b128 v[200:203], v171 offset:32768
	ds_read_b128 v[204:207], v171 offset:33792
	ds_read_b128 v[208:211], v171 offset:34816
	ds_read_b128 v[212:215], v171 offset:35840
	ds_read_b128 v[216:219], v171 offset:36864
	ds_read_b128 v[220:223], v171 offset:37888
	ds_read_b128 v[224:227], v171 offset:38912
	ds_read_b128 v[238:241], v171 offset:39936
	global_load_lds_dwordx4 v[244:245], off
	v_lshl_add_u64 v[244:245], s[36:37], 0, v[134:135]
	s_mov_b32 m0, s46
	s_nop 0
	global_load_lds_dwordx4 v[244:245], off
	s_waitcnt vmcnt(8) lgkmcnt(0)
	s_barrier
	v_mfma_f32_16x16x32_bf16 v[72:75], v[166:169], v[200:203], v[72:75]
	v_mfma_f32_16x16x32_bf16 v[68:71], v[176:179], v[200:203], v[68:71]
	v_mfma_f32_16x16x32_bf16 v[64:67], v[166:169], v[208:211], v[64:67]
	v_mfma_f32_16x16x32_bf16 v[60:63], v[176:179], v[208:211], v[60:63]
	v_mfma_f32_16x16x32_bf16 v[56:59], v[166:169], v[216:219], v[56:59]
	v_mfma_f32_16x16x32_bf16 v[52:55], v[176:179], v[216:219], v[52:55]
	v_mfma_f32_16x16x32_bf16 v[48:51], v[166:169], v[224:227], v[48:51]
	v_mfma_f32_16x16x32_bf16 v[44:47], v[176:179], v[224:227], v[44:47]
	v_mfma_f32_16x16x32_bf16 v[72:75], v[172:175], v[204:207], v[72:75]
	v_mfma_f32_16x16x32_bf16 v[68:71], v[180:183], v[204:207], v[68:71]
	v_mfma_f32_16x16x32_bf16 v[64:67], v[172:175], v[212:215], v[64:67]
	v_mfma_f32_16x16x32_bf16 v[60:63], v[180:183], v[212:215], v[60:63]
	v_mfma_f32_16x16x32_bf16 v[56:59], v[172:175], v[220:223], v[56:59]
	v_mfma_f32_16x16x32_bf16 v[52:55], v[180:183], v[220:223], v[52:55]
	v_mfma_f32_16x16x32_bf16 v[48:51], v[172:175], v[238:241], v[48:51]
	v_mfma_f32_16x16x32_bf16 v[44:47], v[180:183], v[238:241], v[44:47]
	v_mfma_f32_16x16x32_bf16 v[128:131], v[184:187], v[200:203], v[128:131]
	v_mfma_f32_16x16x32_bf16 v[124:127], v[192:195], v[200:203], v[124:127]
	v_mfma_f32_16x16x32_bf16 v[120:123], v[184:187], v[208:211], v[120:123]
	v_mfma_f32_16x16x32_bf16 v[116:119], v[192:195], v[208:211], v[116:119]
	v_mfma_f32_16x16x32_bf16 v[112:115], v[184:187], v[216:219], v[112:115]
	v_mfma_f32_16x16x32_bf16 v[108:111], v[192:195], v[216:219], v[108:111]
	v_mfma_f32_16x16x32_bf16 v[104:107], v[184:187], v[224:227], v[104:107]
	v_mfma_f32_16x16x32_bf16 v[100:103], v[192:195], v[224:227], v[100:103]
	v_mfma_f32_16x16x32_bf16 v[128:131], v[188:191], v[204:207], v[128:131]
	v_mfma_f32_16x16x32_bf16 v[124:127], v[196:199], v[204:207], v[124:127]
	v_mfma_f32_16x16x32_bf16 v[120:123], v[188:191], v[212:215], v[120:123]
	v_mfma_f32_16x16x32_bf16 v[116:119], v[196:199], v[212:215], v[116:119]
	v_mfma_f32_16x16x32_bf16 v[112:115], v[188:191], v[220:223], v[112:115]
	v_mfma_f32_16x16x32_bf16 v[108:111], v[196:199], v[220:223], v[108:111]
	v_mfma_f32_16x16x32_bf16 v[104:107], v[188:191], v[238:241], v[104:107]
	v_mfma_f32_16x16x32_bf16 v[100:103], v[196:199], v[238:241], v[100:103]
	s_barrier
; #define PG8_STAGE(bufoff, gbase, voff) do { _Pragma("unroll") for (int _i = 0; _i < 2; ++_i) \
;         __builtin_amdgcn_global_load_lds((const unsigned*)((const char*)(gbase) + (voff)[_i]), (PG8_LAS unsigned*)(lds + (bufoff) + ldsw + _i * 8192), 16, 0, 0); } while (0)
; #define PG8_LDA(dst, b, h) do { _Pragma("unroll") for (int m = 0; m < 4; ++m) _Pragma("unroll") for (int k = 0; k < 2; ++k) dst[m][k] = *(const PG8_LAS bf16x8*)(lds + PG8_SA(b, h) + aoff + m * 2048 + k * 1024); } while (0)
; #define PG8_MMA(ai, bj, At, Bt) do { __builtin_amdgcn_s_setprio(1); _Pragma("unroll") for (int m = 0; m < 4; ++m) _Pragma("unroll") for (int n = 0; n < 2; ++n) _Pragma("unroll") for (int k = 0; k < 2; ++k) \
;         acc[ai][bj][m][n] = __builtin_amdgcn_mfma_f32_16x16x32_bf16(Bt[n][k], At[m][k], acc[ai][bj][m][n], 0, 0, 0); __builtin_amdgcn_s_setprio(0); } while (0)
; #define PG8_WAIT_V(n) asm volatile("s_waitcnt vmcnt(" #n ")" ::: "memory")
; #define PG8_WAIT_L(n) asm volatile("s_waitcnt lgkmcnt(" #n ")" ::: "memory")
; #define PG8_BAR __builtin_amdgcn_s_barrier()
; #define PG8_SCHED __builtin_amdgcn_sched_barrier(0)
; template <class Epi, class Sched, bool ALIGN_EPI = false, bool SP2 = false>
; __device__ __forceinline__ void gemm_phase(PG8_LAS unsigned char* lds, const Gemm g, const Sched& S, const Epi& E, const int tid) {
;     ...
;             PG8_LDA(At, 1, 1); PG8_STAGE(PG8_SB(1, 0), b3, voffB); PG8_STAGE(PG8_SB(1, 1), b3 + hstep, voffB); PG8_STAGE(PG8_SA(1, 0), a3, voffA);
;             PG8_WAIT_V(8); PG8_WAIT_L(0); PG8_BAR; PG8_MMA(1, 0, At, B0); PG8_MMA(1, 1, At, B1); PG8_BAR; PG8_SCHED;
;     ...
;         if constexpr (ALIGN_EPI) { if (wr == 0) PG8_BAR; }
	s_add_i32 s36, s55, s43
	v_lshl_add_u64 v[146:147], v[146:147], 0, s[0:1]
	s_mov_b32 m0, s36
	ds_read_b128 v[200:203], v171 offset:49152
	ds_read_b128 v[204:207], v171 offset:50176
	ds_read_b128 v[208:211], v171 offset:51200
	ds_read_b128 v[212:215], v171 offset:52224
	ds_read_b128 v[216:219], v171 offset:53248
	ds_read_b128 v[220:223], v171 offset:54272
	ds_read_b128 v[224:227], v171 offset:55296
	ds_read_b128 v[238:241], v171 offset:56320
	global_load_lds_dwordx4 v[146:147], off
	s_add_i32 m0, s36, 0x2000
	s_add_u32 s26, s26, 0x40080
	v_lshl_add_u64 v[146:147], v[148:149], 0, s[0:1]
	s_addc_u32 s27, s27, 0
	s_add_i32 s36, s56, s43
	global_load_lds_dwordx4 v[146:147], off
	v_lshl_add_u64 v[146:147], s[26:27], 0, v[132:133]
	s_mov_b32 m0, s36
	s_nop 0
	global_load_lds_dwordx4 v[146:147], off
	v_lshl_add_u64 v[146:147], s[26:27], 0, v[136:137]
	s_add_i32 m0, s36, 0x2000
	s_nop 0
	global_load_lds_dwordx4 v[146:147], off
	v_lshl_add_u64 v[146:147], v[150:151], 0, s[0:1]
	s_mov_b32 m0, s48
	s_nop 0
	global_load_lds_dwordx4 v[146:147], off
	v_lshl_add_u64 v[146:147], v[242:243], 0, s[0:1]
	s_mov_b32 m0, s49
	s_nop 0
	global_load_lds_dwordx4 v[146:147], off
	s_waitcnt vmcnt(8) lgkmcnt(0)
	s_barrier
	v_mfma_f32_16x16x32_bf16 v[40:43], v[166:169], v[200:203], v[40:43]
	v_mfma_f32_16x16x32_bf16 v[36:39], v[176:179], v[200:203], v[36:39]
	v_mfma_f32_16x16x32_bf16 v[32:35], v[166:169], v[208:211], v[32:35]
	v_mfma_f32_16x16x32_bf16 v[28:31], v[176:179], v[208:211], v[28:31]
	v_mfma_f32_16x16x32_bf16 v[24:27], v[166:169], v[216:219], v[24:27]
	v_mfma_f32_16x16x32_bf16 v[20:23], v[176:179], v[216:219], v[20:23]
	v_mfma_f32_16x16x32_bf16 v[8:11], v[166:169], v[224:227], v[8:11]
	v_mfma_f32_16x16x32_bf16 v[4:7], v[176:179], v[224:227], v[4:7]
	v_mfma_f32_16x16x32_bf16 v[40:43], v[172:175], v[204:207], v[40:43]
	v_mfma_f32_16x16x32_bf16 v[36:39], v[180:183], v[204:207], v[36:39]
	v_mfma_f32_16x16x32_bf16 v[32:35], v[172:175], v[212:215], v[32:35]
	v_mfma_f32_16x16x32_bf16 v[28:31], v[180:183], v[212:215], v[28:31]
	v_mfma_f32_16x16x32_bf16 v[24:27], v[172:175], v[220:223], v[24:27]
	v_mfma_f32_16x16x32_bf16 v[20:23], v[180:183], v[220:223], v[20:23]
	v_mfma_f32_16x16x32_bf16 v[8:11], v[172:175], v[238:241], v[8:11]
	v_mfma_f32_16x16x32_bf16 v[4:7], v[180:183], v[238:241], v[4:7]
	v_mfma_f32_16x16x32_bf16 v[96:99], v[184:187], v[200:203], v[96:99]
	v_mfma_f32_16x16x32_bf16 v[92:95], v[192:195], v[200:203], v[92:95]
	v_mfma_f32_16x16x32_bf16 v[88:91], v[184:187], v[208:211], v[88:91]
	v_mfma_f32_16x16x32_bf16 v[84:87], v[192:195], v[208:211], v[84:87]
	v_mfma_f32_16x16x32_bf16 v[80:83], v[184:187], v[216:219], v[80:83]
	v_mfma_f32_16x16x32_bf16 v[76:79], v[192:195], v[216:219], v[76:79]
	v_mfma_f32_16x16x32_bf16 v[16:19], v[184:187], v[224:227], v[16:19]
	v_mfma_f32_16x16x32_bf16 v[12:15], v[192:195], v[224:227], v[12:15]
	v_mfma_f32_16x16x32_bf16 v[96:99], v[188:191], v[204:207], v[96:99]
	v_mfma_f32_16x16x32_bf16 v[92:95], v[196:199], v[204:207], v[92:95]
	v_mfma_f32_16x16x32_bf16 v[88:91], v[188:191], v[212:215], v[88:91]
	v_mfma_f32_16x16x32_bf16 v[84:87], v[196:199], v[212:215], v[84:87]
	v_mfma_f32_16x16x32_bf16 v[80:83], v[188:191], v[220:223], v[80:83]
	v_mfma_f32_16x16x32_bf16 v[76:79], v[196:199], v[220:223], v[76:79]
	v_mfma_f32_16x16x32_bf16 v[16:19], v[188:191], v[238:241], v[16:19]
	v_mfma_f32_16x16x32_bf16 v[12:15], v[196:199], v[238:241], v[12:15]
	s_barrier
	s_add_i32 s54, s54, 2
	s_add_u32 s2, s2, 0x100
	s_addc_u32 s3, s3, 0
	s_add_u32 s52, s52, 0x100
	s_addc_u32 s53, s53, 0
	s_cmp_gt_u32 s54, 13
	s_cbranch_scc0 .LBB0_293
	s_and_b64 vcc, exec, s[10:11]
	s_cbranch_vccz .LBB0_296
	s_barrier

; #define PG8_STAGE(bufoff, gbase, voff) do { _Pragma("unroll") for (int _i = 0; _i < 2; ++_i) \
;         __builtin_amdgcn_global_load_lds((const unsigned*)((const char*)(gbase) + (voff)[_i]), (PG8_LAS unsigned*)(lds + (bufoff) + ldsw + _i * 8192), 16, 0, 0); } while (0)
; #define PG8_LDA(dst, b, h) do { _Pragma("unroll") for (int m = 0; m < 4; ++m) _Pragma("unroll") for (int k = 0; k < 2; ++k) dst[m][k] = *(const PG8_LAS bf16x8*)(lds + PG8_SA(b, h) + aoff + m * 2048 + k * 1024); } while (0)
; #define PG8_LDB(dst, b, h) do { _Pragma("unroll") for (int n = 0; n < 2; ++n) _Pragma("unroll") for (int k = 0; k < 2; ++k) dst[n][k] = *(const PG8_LAS bf16x8*)(lds + PG8_SB(b, h) + boff + n * 2048 + k * 1024); } while (0)
; #define PG8_MMA(ai, bj, At, Bt) do { __builtin_amdgcn_s_setprio(1); _Pragma("unroll") for (int m = 0; m < 4; ++m) _Pragma("unroll") for (int n = 0; n < 2; ++n) _Pragma("unroll") for (int k = 0; k < 2; ++k) \
;         acc[ai][bj][m][n] = __builtin_amdgcn_mfma_f32_16x16x32_bf16(Bt[n][k], At[m][k], acc[ai][bj][m][n], 0, 0, 0); __builtin_amdgcn_s_setprio(0); } while (0)
; #define PG8_WAIT_V(n) asm volatile("s_waitcnt vmcnt(" #n ")" ::: "memory")
; #define PG8_WAIT_L(n) asm volatile("s_waitcnt lgkmcnt(" #n ")" ::: "memory")
; #define PG8_BAR __builtin_amdgcn_s_barrier()
; #define PG8_SCHED __builtin_amdgcn_sched_barrier(0)
; template <class Epi, class Sched, bool ALIGN_EPI = false, bool SP2 = false>
; __device__ __forceinline__ void gemm_phase(PG8_LAS unsigned char* lds, const Gemm g, const Sched& S, const Epi& E, const int tid) {
;     ...
;             const bool last = (t == nt - 2);
;             const char* a1 = cA + (size_t)(t + 1) * kstep;
;             const char* a2 = last ? nA : cA + (size_t)(t + 2) * kstep; const char* b2 = last ? nB : cB + (size_t)(t + 2) * kstep;
;             const char* a3 = a2 + kstep; const char* b3 = b2 + kstep;
;             if (last && has_next) S.a_ready(nxt);
;             if constexpr (SP2) {
;             PG8_LDB(B0, 0, 0); PG8_LDB(B1, 0, 1); PG8_SCHED; PG8_LDA(At, 0, 0); PG8_STAGE(PG8_SA(1, 1), a1 + hstep, voffA);
;             PG8_WAIT_V(8); PG8_WAIT_L(0); PG8_BAR; PG8_MMA(0, 0, At, B0); PG8_MMA(0, 1, At, B1); PG8_BAR; PG8_SCHED;
;             PG8_LDA(At, 0, 1); PG8_STAGE(PG8_SB(0, 0), b2, voffB); PG8_STAGE(PG8_SB(0, 1), b2 + hstep, voffB); PG8_STAGE(PG8_SA(0, 0), a2, voffA);
.LBB0_476:
	s_add_i32 s80, s58, 2
	s_add_u32 s81, s6, 0x80
	s_addc_u32 s59, s7, 0
	s_add_i32 s87, 0, 0x10000
	s_cmp_eq_u32 s70, s58
	s_cselect_b32 s59, s55, s59
	s_cselect_b32 s58, s54, s81
	v_add_u32_e32 v144, s87, v184
	s_cselect_b32 s83, s57, s79
	s_cselect_b32 s82, s56, s78
	s_add_i32 s81, 0, 0x14000
	ds_read_b128 v[132:135], v144
	ds_read_b128 v[136:139], v144 offset:1024
	ds_read_b128 v[140:143], v144 offset:2048
	ds_read_b128 v[174:177], v144 offset:3072
	v_add_u32_e32 v144, s81, v184
	ds_read_b128 v[178:181], v144
	ds_read_b128 v[188:191], v144 offset:1024
	ds_read_b128 v[192:195], v144 offset:2048
	ds_read_b128 v[196:199], v144 offset:3072
	v_lshl_add_u64 v[144:145], s[6:7], 0, v[170:171]
	s_add_i32 m0, s62, 0xc000
	ds_read_b128 v[200:203], v186
	ds_read_b128 v[204:207], v186 offset:1024
	ds_read_b128 v[208:211], v186 offset:2048
	ds_read_b128 v[212:215], v186 offset:3072
	ds_read_b128 v[216:219], v186 offset:4096
	ds_read_b128 v[220:223], v186 offset:5120
	ds_read_b128 v[224:227], v186 offset:6144
	ds_read_b128 v[238:241], v186 offset:7168
	global_load_lds_dwordx4 v[144:145], off
	v_lshl_add_u64 v[144:145], s[6:7], 0, v[172:173]
	s_add_i32 m0, s62, 0xe000
	s_nop 0
	global_load_lds_dwordx4 v[144:145], off
	s_waitcnt vmcnt(8) lgkmcnt(0)
	s_barrier
	v_mfma_f32_16x16x32_bf16 v[128:131], v[132:135], v[200:203], v[128:131]
	v_mfma_f32_16x16x32_bf16 v[124:127], v[140:143], v[200:203], v[124:127]
	v_mfma_f32_16x16x32_bf16 v[112:115], v[132:135], v[208:211], v[112:115]
	v_mfma_f32_16x16x32_bf16 v[108:111], v[140:143], v[208:211], v[108:111]
	v_mfma_f32_16x16x32_bf16 v[96:99], v[132:135], v[216:219], v[96:99]
	v_mfma_f32_16x16x32_bf16 v[92:95], v[140:143], v[216:219], v[92:95]
	v_mfma_f32_16x16x32_bf16 v[80:83], v[132:135], v[224:227], v[80:83]
	v_mfma_f32_16x16x32_bf16 v[76:79], v[140:143], v[224:227], v[76:79]
	v_mfma_f32_16x16x32_bf16 v[128:131], v[136:139], v[204:207], v[128:131]
	v_mfma_f32_16x16x32_bf16 v[124:127], v[174:177], v[204:207], v[124:127]
	v_mfma_f32_16x16x32_bf16 v[112:115], v[136:139], v[212:215], v[112:115]
	v_mfma_f32_16x16x32_bf16 v[108:111], v[174:177], v[212:215], v[108:111]
	v_mfma_f32_16x16x32_bf16 v[96:99], v[136:139], v[220:223], v[96:99]
	v_mfma_f32_16x16x32_bf16 v[92:95], v[174:177], v[220:223], v[92:95]
	v_mfma_f32_16x16x32_bf16 v[80:83], v[136:139], v[238:241], v[80:83]
	v_mfma_f32_16x16x32_bf16 v[76:79], v[174:177], v[238:241], v[76:79]
	v_mfma_f32_16x16x32_bf16 v[120:123], v[178:181], v[200:203], v[120:123]
	v_mfma_f32_16x16x32_bf16 v[116:119], v[192:195], v[200:203], v[116:119]
	v_mfma_f32_16x16x32_bf16 v[104:107], v[178:181], v[208:211], v[104:107]
	v_mfma_f32_16x16x32_bf16 v[100:103], v[192:195], v[208:211], v[100:103]
	v_mfma_f32_16x16x32_bf16 v[88:91], v[178:181], v[216:219], v[88:91]
	v_mfma_f32_16x16x32_bf16 v[84:87], v[192:195], v[216:219], v[84:87]
	v_mfma_f32_16x16x32_bf16 v[72:75], v[178:181], v[224:227], v[72:75]
	v_mfma_f32_16x16x32_bf16 v[68:71], v[192:195], v[224:227], v[68:71]
	v_mfma_f32_16x16x32_bf16 v[120:123], v[188:191], v[204:207], v[120:123]
	v_mfma_f32_16x16x32_bf16 v[116:119], v[196:199], v[204:207], v[116:119]
	v_mfma_f32_16x16x32_bf16 v[104:107], v[188:191], v[212:215], v[104:107]
	v_mfma_f32_16x16x32_bf16 v[100:103], v[196:199], v[212:215], v[100:103]
	v_mfma_f32_16x16x32_bf16 v[88:91], v[188:191], v[220:223], v[88:91]
	v_mfma_f32_16x16x32_bf16 v[84:87], v[196:199], v[220:223], v[84:87]
	v_mfma_f32_16x16x32_bf16 v[72:75], v[188:191], v[238:241], v[72:75]
	v_mfma_f32_16x16x32_bf16 v[68:71], v[196:199], v[238:241], v[68:71]
	s_barrier
	s_add_i32 s87, s87, s61
	v_lshl_add_u64 v[144:145], s[82:83], 0, v[146:147]
	s_mov_b32 m0, s87
	ds_read_b128 v[200:203], v186 offset:16384
	ds_read_b128 v[204:207], v186 offset:17408
	ds_read_b128 v[208:211], v186 offset:18432
	ds_read_b128 v[212:215], v186 offset:19456
	ds_read_b128 v[216:219], v186 offset:20480
	ds_read_b128 v[220:223], v186 offset:21504
	ds_read_b128 v[224:227], v186 offset:22528
	ds_read_b128 v[238:241], v186 offset:23552
	global_load_lds_dwordx4 v[144:145], off
	s_add_i32 m0, s87, 0x2000
	v_lshl_add_u64 v[242:243], s[82:83], 0, v[168:169]
	s_add_u32 s82, s82, s14
	s_addc_u32 s83, s83, 0
	s_add_i32 s81, s81, s61
	global_load_lds_dwordx4 v[242:243], off
	v_lshl_add_u64 v[244:245], s[82:83], 0, v[146:147]
	s_mov_b32 m0, s81
	v_lshl_add_u64 v[246:247], s[82:83], 0, v[168:169]
	global_load_lds_dwordx4 v[244:245], off
	s_add_i32 m0, s81, 0x2000
	v_lshl_add_u64 v[248:249], s[58:59], 0, v[0:1]
	global_load_lds_dwordx4 v[246:247], off
	s_mov_b32 m0, s62
	v_lshl_add_u64 v[148:149], s[58:59], 0, v[166:167]
	global_load_lds_dwordx4 v[248:249], off
	s_mov_b32 m0, s63
	s_nop 0
	global_load_lds_dwordx4 v[148:149], off
	s_waitcnt vmcnt(8) lgkmcnt(0)
	s_barrier
; #define PG8_STAGE(bufoff, gbase, voff) do { _Pragma("unroll") for (int _i = 0; _i < 2; ++_i) \
;         __builtin_amdgcn_global_load_lds((const unsigned*)((const char*)(gbase) + (voff)[_i]), (PG8_LAS unsigned*)(lds + (bufoff) + ldsw + _i * 8192), 16, 0, 0); } while (0)
; #define PG8_LDA(dst, b, h) do { _Pragma("unroll") for (int m = 0; m < 4; ++m) _Pragma("unroll") for (int k = 0; k < 2; ++k) dst[m][k] = *(const PG8_LAS bf16x8*)(lds + PG8_SA(b, h) + aoff + m * 2048 + k * 1024); } while (0)
; #define PG8_LDB(dst, b, h) do { _Pragma("unroll") for (int n = 0; n < 2; ++n) _Pragma("unroll") for (int k = 0; k < 2; ++k) dst[n][k] = *(const PG8_LAS bf16x8*)(lds + PG8_SB(b, h) + boff + n * 2048 + k * 1024); } while (0)
; #define PG8_MMA(ai, bj, At, Bt) do { __builtin_amdgcn_s_setprio(1); _Pragma("unroll") for (int m = 0; m < 4; ++m) _Pragma("unroll") for (int n = 0; n < 2; ++n) _Pragma("unroll") for (int k = 0; k < 2; ++k) \
;         acc[ai][bj][m][n] = __builtin_amdgcn_mfma_f32_16x16x32_bf16(Bt[n][k], At[m][k], acc[ai][bj][m][n], 0, 0, 0); __builtin_amdgcn_s_setprio(0); } while (0)
; #define PG8_WAIT_V(n) asm volatile("s_waitcnt vmcnt(" #n ")" ::: "memory")
; #define PG8_WAIT_L(n) asm volatile("s_waitcnt lgkmcnt(" #n ")" ::: "memory")
; #define PG8_BAR __builtin_amdgcn_s_barrier()
; #define PG8_SCHED __builtin_amdgcn_sched_barrier(0)
; template <class Epi, class Sched, bool ALIGN_EPI = false, bool SP2 = false>
; __device__ __forceinline__ void gemm_phase(PG8_LAS unsigned char* lds, const Gemm g, const Sched& S, const Epi& E, const int tid) {
;     ...
;             PG8_WAIT_V(8); PG8_WAIT_L(0); PG8_BAR; PG8_MMA(1, 0, At, B0); PG8_MMA(1, 1, At, B1); PG8_BAR; PG8_SCHED;
;             PG8_LDB(B0, 1, 0); PG8_LDB(B1, 1, 1); PG8_SCHED; PG8_LDA(At, 1, 0); PG8_STAGE(PG8_SA(0, 1), a2 + hstep, voffA);
;             PG8_WAIT_V(8); PG8_WAIT_L(0); PG8_BAR; PG8_MMA(0, 0, At, B0); PG8_MMA(0, 1, At, B1); PG8_BAR; PG8_SCHED;
	v_mfma_f32_16x16x32_bf16 v[64:67], v[132:135], v[200:203], v[64:67]
	v_mfma_f32_16x16x32_bf16 v[60:63], v[140:143], v[200:203], v[60:63]
	v_mfma_f32_16x16x32_bf16 v[48:51], v[132:135], v[208:211], v[48:51]
	v_mfma_f32_16x16x32_bf16 v[44:47], v[140:143], v[208:211], v[44:47]
	v_mfma_f32_16x16x32_bf16 v[32:35], v[132:135], v[216:219], v[32:35]
	v_mfma_f32_16x16x32_bf16 v[28:31], v[140:143], v[216:219], v[28:31]
	v_mfma_f32_16x16x32_bf16 v[16:19], v[132:135], v[224:227], v[16:19]
	v_mfma_f32_16x16x32_bf16 v[12:15], v[140:143], v[224:227], v[12:15]
	v_mfma_f32_16x16x32_bf16 v[64:67], v[136:139], v[204:207], v[64:67]
	v_mfma_f32_16x16x32_bf16 v[60:63], v[174:177], v[204:207], v[60:63]
	v_mfma_f32_16x16x32_bf16 v[48:51], v[136:139], v[212:215], v[48:51]
	v_mfma_f32_16x16x32_bf16 v[44:47], v[174:177], v[212:215], v[44:47]
	v_mfma_f32_16x16x32_bf16 v[32:35], v[136:139], v[220:223], v[32:35]
	v_mfma_f32_16x16x32_bf16 v[28:31], v[174:177], v[220:223], v[28:31]
	v_mfma_f32_16x16x32_bf16 v[16:19], v[136:139], v[238:241], v[16:19]
	v_mfma_f32_16x16x32_bf16 v[12:15], v[174:177], v[238:241], v[12:15]
	v_mfma_f32_16x16x32_bf16 v[56:59], v[178:181], v[200:203], v[56:59]
	v_mfma_f32_16x16x32_bf16 v[52:55], v[192:195], v[200:203], v[52:55]
	v_mfma_f32_16x16x32_bf16 v[40:43], v[178:181], v[208:211], v[40:43]
	v_mfma_f32_16x16x32_bf16 v[36:39], v[192:195], v[208:211], v[36:39]
	v_mfma_f32_16x16x32_bf16 v[24:27], v[178:181], v[216:219], v[24:27]
	v_mfma_f32_16x16x32_bf16 v[20:23], v[192:195], v[216:219], v[20:23]
	v_mfma_f32_16x16x32_bf16 v[8:11], v[178:181], v[224:227], v[8:11]
	v_mfma_f32_16x16x32_bf16 v[4:7], v[192:195], v[224:227], v[4:7]
	v_mfma_f32_16x16x32_bf16 v[56:59], v[188:191], v[204:207], v[56:59]
	v_mfma_f32_16x16x32_bf16 v[52:55], v[196:199], v[204:207], v[52:55]
	v_mfma_f32_16x16x32_bf16 v[40:43], v[188:191], v[212:215], v[40:43]
	v_mfma_f32_16x16x32_bf16 v[36:39], v[196:199], v[212:215], v[36:39]
	v_mfma_f32_16x16x32_bf16 v[24:27], v[188:191], v[220:223], v[24:27]
	v_mfma_f32_16x16x32_bf16 v[20:23], v[196:199], v[220:223], v[20:23]
	v_mfma_f32_16x16x32_bf16 v[8:11], v[188:191], v[238:241], v[8:11]
	v_mfma_f32_16x16x32_bf16 v[4:7], v[196:199], v[238:241], v[4:7]
	s_barrier
	s_add_i32 s81, 0, 0x18000
	v_add_u32_e32 v150, s81, v184
	s_add_i32 s82, 0, 0x1c000
	ds_read_b128 v[132:135], v150
	ds_read_b128 v[136:139], v150 offset:1024
	ds_read_b128 v[140:143], v150 offset:2048
	ds_read_b128 v[174:177], v150 offset:3072
	v_add_u32_e32 v150, s82, v184
	ds_read_b128 v[178:181], v150
	ds_read_b128 v[188:191], v150 offset:1024
	ds_read_b128 v[192:195], v150 offset:2048
	ds_read_b128 v[196:199], v150 offset:3072
	s_add_u32 s58, s58, s14
	s_addc_u32 s59, s59, 0
	s_mov_b32 m0, s64
	v_lshl_add_u64 v[150:151], s[58:59], 0, v[0:1]
	ds_read_b128 v[200:203], v186 offset:32768
	ds_read_b128 v[204:207], v186 offset:33792
	ds_read_b128 v[208:211], v186 offset:34816
	ds_read_b128 v[212:215], v186 offset:35840
	ds_read_b128 v[216:219], v186 offset:36864
	ds_read_b128 v[220:223], v186 offset:37888
	ds_read_b128 v[224:227], v186 offset:38912
	ds_read_b128 v[238:241], v186 offset:39936
	global_load_lds_dwordx4 v[150:151], off
	v_lshl_add_u64 v[150:151], s[58:59], 0, v[166:167]
	s_mov_b32 m0, s65
	s_nop 0
	global_load_lds_dwordx4 v[150:151], off
	s_waitcnt vmcnt(8) lgkmcnt(0)
	s_barrier
	v_mfma_f32_16x16x32_bf16 v[128:131], v[132:135], v[200:203], v[128:131]
	v_mfma_f32_16x16x32_bf16 v[124:127], v[140:143], v[200:203], v[124:127]
	v_mfma_f32_16x16x32_bf16 v[112:115], v[132:135], v[208:211], v[112:115]
	v_mfma_f32_16x16x32_bf16 v[108:111], v[140:143], v[208:211], v[108:111]
	v_mfma_f32_16x16x32_bf16 v[96:99], v[132:135], v[216:219], v[96:99]
	v_mfma_f32_16x16x32_bf16 v[92:95], v[140:143], v[216:219], v[92:95]
	v_mfma_f32_16x16x32_bf16 v[80:83], v[132:135], v[224:227], v[80:83]
	v_mfma_f32_16x16x32_bf16 v[76:79], v[140:143], v[224:227], v[76:79]
	v_mfma_f32_16x16x32_bf16 v[128:131], v[136:139], v[204:207], v[128:131]
	v_mfma_f32_16x16x32_bf16 v[124:127], v[174:177], v[204:207], v[124:127]
	v_mfma_f32_16x16x32_bf16 v[112:115], v[136:139], v[212:215], v[112:115]
	v_mfma_f32_16x16x32_bf16 v[108:111], v[174:177], v[212:215], v[108:111]
	v_mfma_f32_16x16x32_bf16 v[96:99], v[136:139], v[220:223], v[96:99]
	v_mfma_f32_16x16x32_bf16 v[92:95], v[174:177], v[220:223], v[92:95]
	v_mfma_f32_16x16x32_bf16 v[80:83], v[136:139], v[238:241], v[80:83]
	v_mfma_f32_16x16x32_bf16 v[76:79], v[174:177], v[238:241], v[76:79]
	v_mfma_f32_16x16x32_bf16 v[120:123], v[178:181], v[200:203], v[120:123]
	v_mfma_f32_16x16x32_bf16 v[116:119], v[192:195], v[200:203], v[116:119]
	v_mfma_f32_16x16x32_bf16 v[104:107], v[178:181], v[208:211], v[104:107]
	v_mfma_f32_16x16x32_bf16 v[100:103], v[192:195], v[208:211], v[100:103]
	v_mfma_f32_16x16x32_bf16 v[88:91], v[178:181], v[216:219], v[88:91]
	v_mfma_f32_16x16x32_bf16 v[84:87], v[192:195], v[216:219], v[84:87]
	v_mfma_f32_16x16x32_bf16 v[72:75], v[178:181], v[224:227], v[72:75]
	v_mfma_f32_16x16x32_bf16 v[68:71], v[192:195], v[224:227], v[68:71]
	v_mfma_f32_16x16x32_bf16 v[120:123], v[188:191], v[204:207], v[120:123]
	v_mfma_f32_16x16x32_bf16 v[116:119], v[196:199], v[204:207], v[116:119]
	v_mfma_f32_16x16x32_bf16 v[104:107], v[188:191], v[212:215], v[104:107]
	v_mfma_f32_16x16x32_bf16 v[100:103], v[196:199], v[212:215], v[100:103]
	v_mfma_f32_16x16x32_bf16 v[88:91], v[188:191], v[220:223], v[88:91]
	v_mfma_f32_16x16x32_bf16 v[84:87], v[196:199], v[220:223], v[84:87]
	v_mfma_f32_16x16x32_bf16 v[72:75], v[188:191], v[238:241], v[72:75]
	v_mfma_f32_16x16x32_bf16 v[68:71], v[196:199], v[238:241], v[68:71]
	s_barrier
; #define PG8_STAGE(bufoff, gbase, voff) do { _Pragma("unroll") for (int _i = 0; _i < 2; ++_i) \
;         __builtin_amdgcn_global_load_lds((const unsigned*)((const char*)(gbase) + (voff)[_i]), (PG8_LAS unsigned*)(lds + (bufoff) + ldsw + _i * 8192), 16, 0, 0); } while (0)
; #define PG8_LDA(dst, b, h) do { _Pragma("unroll") for (int m = 0; m < 4; ++m) _Pragma("unroll") for (int k = 0; k < 2; ++k) dst[m][k] = *(const PG8_LAS bf16x8*)(lds + PG8_SA(b, h) + aoff + m * 2048 + k * 1024); } while (0)
; #define PG8_MMA(ai, bj, At, Bt) do { __builtin_amdgcn_s_setprio(1); _Pragma("unroll") for (int m = 0; m < 4; ++m) _Pragma("unroll") for (int n = 0; n < 2; ++n) _Pragma("unroll") for (int k = 0; k < 2; ++k) \
;         acc[ai][bj][m][n] = __builtin_amdgcn_mfma_f32_16x16x32_bf16(Bt[n][k], At[m][k], acc[ai][bj][m][n], 0, 0, 0); __builtin_amdgcn_s_setprio(0); } while (0)
; #define PG8_WAIT_V(n) asm volatile("s_waitcnt vmcnt(" #n ")" ::: "memory")
; #define PG8_WAIT_L(n) asm volatile("s_waitcnt lgkmcnt(" #n ")" ::: "memory")
; #define PG8_BAR __builtin_amdgcn_s_barrier()
; #define PG8_SCHED __builtin_amdgcn_sched_barrier(0)
; template <class Epi, class Sched, bool ALIGN_EPI = false, bool SP2 = false>
; __device__ __forceinline__ void gemm_phase(PG8_LAS unsigned char* lds, const Gemm g, const Sched& S, const Epi& E, const int tid) {
;     ...
;             PG8_LDA(At, 1, 1); PG8_STAGE(PG8_SB(1, 0), b3, voffB); PG8_STAGE(PG8_SB(1, 1), b3 + hstep, voffB); PG8_STAGE(PG8_SA(1, 0), a3, voffA);
;             PG8_WAIT_V(8); PG8_WAIT_L(0); PG8_BAR; PG8_MMA(1, 0, At, B0); PG8_MMA(1, 1, At, B1); PG8_BAR; PG8_SCHED;
;     ...
;         if constexpr (ALIGN_EPI) { if (wr == 0) PG8_BAR; }
	s_add_i32 s58, s81, s61
	v_lshl_add_u64 v[144:145], v[144:145], 0, s[0:1]
	s_mov_b32 m0, s58
	ds_read_b128 v[200:203], v186 offset:49152
	ds_read_b128 v[204:207], v186 offset:50176
	ds_read_b128 v[208:211], v186 offset:51200
	ds_read_b128 v[212:215], v186 offset:52224
	ds_read_b128 v[216:219], v186 offset:53248
	ds_read_b128 v[220:223], v186 offset:54272
	ds_read_b128 v[224:227], v186 offset:55296
	ds_read_b128 v[238:241], v186 offset:56320
	global_load_lds_dwordx4 v[144:145], off
	v_lshl_add_u64 v[144:145], v[242:243], 0, s[0:1]
	s_add_i32 m0, s58, 0x2000
	s_add_i32 s58, s82, s61
	global_load_lds_dwordx4 v[144:145], off
	v_lshl_add_u64 v[144:145], v[244:245], 0, s[0:1]
	s_mov_b32 m0, s58
	s_nop 0
	global_load_lds_dwordx4 v[144:145], off
	v_lshl_add_u64 v[144:145], v[246:247], 0, s[0:1]
	s_add_i32 m0, s58, 0x2000
	s_nop 0
	global_load_lds_dwordx4 v[144:145], off
	v_lshl_add_u64 v[144:145], v[248:249], 0, s[0:1]
	s_mov_b32 m0, s66
	s_nop 0
	global_load_lds_dwordx4 v[144:145], off
	v_lshl_add_u64 v[144:145], v[148:149], 0, s[0:1]
	s_mov_b32 m0, s67
	s_nop 0
	global_load_lds_dwordx4 v[144:145], off
	s_waitcnt vmcnt(8) lgkmcnt(0)
	s_barrier
	v_mfma_f32_16x16x32_bf16 v[64:67], v[132:135], v[200:203], v[64:67]
	v_mfma_f32_16x16x32_bf16 v[60:63], v[140:143], v[200:203], v[60:63]
	v_mfma_f32_16x16x32_bf16 v[48:51], v[132:135], v[208:211], v[48:51]
	v_mfma_f32_16x16x32_bf16 v[44:47], v[140:143], v[208:211], v[44:47]
	v_mfma_f32_16x16x32_bf16 v[32:35], v[132:135], v[216:219], v[32:35]
	v_mfma_f32_16x16x32_bf16 v[28:31], v[140:143], v[216:219], v[28:31]
	v_mfma_f32_16x16x32_bf16 v[16:19], v[132:135], v[224:227], v[16:19]
	v_mfma_f32_16x16x32_bf16 v[12:15], v[140:143], v[224:227], v[12:15]
	v_mfma_f32_16x16x32_bf16 v[64:67], v[136:139], v[204:207], v[64:67]
	v_mfma_f32_16x16x32_bf16 v[60:63], v[174:177], v[204:207], v[60:63]
	v_mfma_f32_16x16x32_bf16 v[48:51], v[136:139], v[212:215], v[48:51]
	v_mfma_f32_16x16x32_bf16 v[44:47], v[174:177], v[212:215], v[44:47]
	v_mfma_f32_16x16x32_bf16 v[32:35], v[136:139], v[220:223], v[32:35]
	v_mfma_f32_16x16x32_bf16 v[28:31], v[174:177], v[220:223], v[28:31]
	v_mfma_f32_16x16x32_bf16 v[16:19], v[136:139], v[238:241], v[16:19]
	v_mfma_f32_16x16x32_bf16 v[12:15], v[174:177], v[238:241], v[12:15]
	v_mfma_f32_16x16x32_bf16 v[56:59], v[178:181], v[200:203], v[56:59]
	v_mfma_f32_16x16x32_bf16 v[52:55], v[192:195], v[200:203], v[52:55]
	v_mfma_f32_16x16x32_bf16 v[40:43], v[178:181], v[208:211], v[40:43]
	v_mfma_f32_16x16x32_bf16 v[36:39], v[192:195], v[208:211], v[36:39]
	v_mfma_f32_16x16x32_bf16 v[24:27], v[178:181], v[216:219], v[24:27]
	v_mfma_f32_16x16x32_bf16 v[20:23], v[192:195], v[216:219], v[20:23]
	v_mfma_f32_16x16x32_bf16 v[8:11], v[178:181], v[224:227], v[8:11]
	v_mfma_f32_16x16x32_bf16 v[4:7], v[192:195], v[224:227], v[4:7]
	v_mfma_f32_16x16x32_bf16 v[56:59], v[188:191], v[204:207], v[56:59]
	v_mfma_f32_16x16x32_bf16 v[52:55], v[196:199], v[204:207], v[52:55]
	v_mfma_f32_16x16x32_bf16 v[40:43], v[188:191], v[212:215], v[40:43]
	v_mfma_f32_16x16x32_bf16 v[36:39], v[196:199], v[212:215], v[36:39]
	v_mfma_f32_16x16x32_bf16 v[24:27], v[188:191], v[220:223], v[24:27]
	v_mfma_f32_16x16x32_bf16 v[20:23], v[196:199], v[220:223], v[20:23]
	v_mfma_f32_16x16x32_bf16 v[8:11], v[188:191], v[238:241], v[8:11]
	v_mfma_f32_16x16x32_bf16 v[4:7], v[196:199], v[238:241], v[4:7]
	s_barrier
	s_add_u32 s6, s6, 0x100
	s_addc_u32 s7, s7, 0
	s_add_u32 s78, s78, 0x100
	s_addc_u32 s79, s79, 0
	s_cmp_ge_u32 s80, s69
	s_mov_b32 s58, s80
	s_cbranch_scc0 .LBB0_476
	s_and_b64 vcc, exec, s[50:51]
	s_cbranch_vccz .LBB0_479
	s_barrier

; #define PG8_STAGE(bufoff, gbase, voff) do { _Pragma("unroll") for (int _i = 0; _i < 2; ++_i) \
;         __builtin_amdgcn_global_load_lds((const unsigned*)((const char*)(gbase) + (voff)[_i]), (PG8_LAS unsigned*)(lds + (bufoff) + ldsw + _i * 8192), 16, 0, 0); } while (0)
; #define PG8_LDA(dst, b, h) do { _Pragma("unroll") for (int m = 0; m < 4; ++m) _Pragma("unroll") for (int k = 0; k < 2; ++k) dst[m][k] = *(const PG8_LAS bf16x8*)(lds + PG8_SA(b, h) + aoff + m * 2048 + k * 1024); } while (0)
; #define PG8_LDB(dst, b, h) do { _Pragma("unroll") for (int n = 0; n < 2; ++n) _Pragma("unroll") for (int k = 0; k < 2; ++k) dst[n][k] = *(const PG8_LAS bf16x8*)(lds + PG8_SB(b, h) + boff + n * 2048 + k * 1024); } while (0)
; #define PG8_MMA(ai, bj, At, Bt) do { __builtin_amdgcn_s_setprio(1); _Pragma("unroll") for (int m = 0; m < 4; ++m) _Pragma("unroll") for (int n = 0; n < 2; ++n) _Pragma("unroll") for (int k = 0; k < 2; ++k) \
;         acc[ai][bj][m][n] = __builtin_amdgcn_mfma_f32_16x16x32_bf16(Bt[n][k], At[m][k], acc[ai][bj][m][n], 0, 0, 0); __builtin_amdgcn_s_setprio(0); } while (0)
; #define PG8_WAIT_V(n) asm volatile("s_waitcnt vmcnt(" #n ")" ::: "memory")
; #define PG8_WAIT_L(n) asm volatile("s_waitcnt lgkmcnt(" #n ")" ::: "memory")
; #define PG8_BAR __builtin_amdgcn_s_barrier()
; #define PG8_SCHED __builtin_amdgcn_sched_barrier(0)
; template <class Epi, class Sched, bool ALIGN_EPI = false, bool SP2 = false>
; __device__ __forceinline__ void gemm_phase(PG8_LAS unsigned char* lds, const Gemm g, const Sched& S, const Epi& E, const int tid) {
;     ...
;             const bool last = (t == nt - 2);
;             const char* a1 = cA + (size_t)(t + 1) * kstep;
;             const char* a2 = last ? nA : cA + (size_t)(t + 2) * kstep; const char* b2 = last ? nB : cB + (size_t)(t + 2) * kstep;
;             const char* a3 = a2 + kstep; const char* b3 = b2 + kstep;
;             if (last && has_next) S.a_ready(nxt);
;             if constexpr (SP2) {
;             PG8_LDB(B0, 0, 0); PG8_LDB(B1, 0, 1); PG8_SCHED; PG8_LDA(At, 0, 0); PG8_STAGE(PG8_SA(1, 1), a1 + hstep, voffA);
;             PG8_WAIT_V(8); PG8_WAIT_L(0); PG8_BAR; PG8_MMA(0, 0, At, B0); PG8_MMA(0, 1, At, B1); PG8_BAR; PG8_SCHED;
;             PG8_LDA(At, 0, 1); PG8_STAGE(PG8_SB(0, 0), b2, voffB); PG8_STAGE(PG8_SB(0, 1), b2 + hstep, voffB); PG8_STAGE(PG8_SA(0, 0), a2, voffA);
.LBB0_522:
	s_add_u32 s20, s18, 0xfffc0080
	s_addc_u32 s21, s19, -1
	s_add_i32 s52, 0, 0x10000
	s_cmp_eq_u32 s51, 12
	s_cselect_b32 s23, s13, s21
	s_cselect_b32 s22, s47, s20
	v_add_u32_e32 v148, s52, v146
	s_cselect_b32 s21, s11, s50
	s_cselect_b32 s20, s48, s49
	s_add_i32 s54, 0, 0x14000
	ds_read_b128 v[142:145], v148
	ds_read_b128 v[166:169], v148 offset:1024
	ds_read_b128 v[170:173], v148 offset:2048
	ds_read_b128 v[174:177], v148 offset:3072
	v_add_u32_e32 v148, s54, v146
	ds_read_b128 v[178:181], v148
	ds_read_b128 v[182:185], v148 offset:1024
	ds_read_b128 v[186:189], v148 offset:2048
	ds_read_b128 v[190:193], v148 offset:3072
	v_lshl_add_u64 v[226:227], s[18:19], 0, v[138:139]
	s_add_i32 m0, s38, 0xc000
	ds_read_b128 v[194:197], v153
	ds_read_b128 v[198:201], v153 offset:1024
	ds_read_b128 v[202:205], v153 offset:2048
	ds_read_b128 v[206:209], v153 offset:3072
	ds_read_b128 v[210:213], v153 offset:4096
	ds_read_b128 v[214:217], v153 offset:5120
	ds_read_b128 v[218:221], v153 offset:6144
	ds_read_b128 v[222:225], v153 offset:7168
	global_load_lds_dwordx4 v[226:227], off
	v_lshl_add_u64 v[226:227], s[18:19], 0, v[140:141]
	s_add_i32 m0, s38, 0xe000
	s_nop 0
	global_load_lds_dwordx4 v[226:227], off
	s_waitcnt vmcnt(8) lgkmcnt(0)
	s_barrier
	v_mfma_f32_16x16x32_bf16 v[128:131], v[142:145], v[194:197], v[128:131]
	v_mfma_f32_16x16x32_bf16 v[120:123], v[170:173], v[194:197], v[120:123]
	v_mfma_f32_16x16x32_bf16 v[112:115], v[142:145], v[202:205], v[112:115]
	v_mfma_f32_16x16x32_bf16 v[104:107], v[170:173], v[202:205], v[104:107]
	v_mfma_f32_16x16x32_bf16 v[96:99], v[142:145], v[210:213], v[96:99]
	v_mfma_f32_16x16x32_bf16 v[88:91], v[170:173], v[210:213], v[88:91]
	v_mfma_f32_16x16x32_bf16 v[80:83], v[142:145], v[218:221], v[80:83]
	v_mfma_f32_16x16x32_bf16 v[72:75], v[170:173], v[218:221], v[72:75]
	v_mfma_f32_16x16x32_bf16 v[128:131], v[166:169], v[198:201], v[128:131]
	v_mfma_f32_16x16x32_bf16 v[120:123], v[174:177], v[198:201], v[120:123]
	v_mfma_f32_16x16x32_bf16 v[112:115], v[166:169], v[206:209], v[112:115]
	v_mfma_f32_16x16x32_bf16 v[104:107], v[174:177], v[206:209], v[104:107]
	v_mfma_f32_16x16x32_bf16 v[96:99], v[166:169], v[214:217], v[96:99]
	v_mfma_f32_16x16x32_bf16 v[88:91], v[174:177], v[214:217], v[88:91]
	v_mfma_f32_16x16x32_bf16 v[80:83], v[166:169], v[222:225], v[80:83]
	v_mfma_f32_16x16x32_bf16 v[72:75], v[174:177], v[222:225], v[72:75]
	v_mfma_f32_16x16x32_bf16 v[124:127], v[178:181], v[194:197], v[124:127]
	v_mfma_f32_16x16x32_bf16 v[116:119], v[186:189], v[194:197], v[116:119]
	v_mfma_f32_16x16x32_bf16 v[108:111], v[178:181], v[202:205], v[108:111]
	v_mfma_f32_16x16x32_bf16 v[100:103], v[186:189], v[202:205], v[100:103]
	v_mfma_f32_16x16x32_bf16 v[92:95], v[178:181], v[210:213], v[92:95]
	v_mfma_f32_16x16x32_bf16 v[84:87], v[186:189], v[210:213], v[84:87]
	v_mfma_f32_16x16x32_bf16 v[76:79], v[178:181], v[218:221], v[76:79]
	v_mfma_f32_16x16x32_bf16 v[68:71], v[186:189], v[218:221], v[68:71]
	v_mfma_f32_16x16x32_bf16 v[124:127], v[182:185], v[198:201], v[124:127]
	v_mfma_f32_16x16x32_bf16 v[116:119], v[190:193], v[198:201], v[116:119]
	v_mfma_f32_16x16x32_bf16 v[108:111], v[182:185], v[206:209], v[108:111]
	v_mfma_f32_16x16x32_bf16 v[100:103], v[190:193], v[206:209], v[100:103]
	v_mfma_f32_16x16x32_bf16 v[92:95], v[182:185], v[214:217], v[92:95]
	v_mfma_f32_16x16x32_bf16 v[84:87], v[190:193], v[214:217], v[84:87]
	v_mfma_f32_16x16x32_bf16 v[76:79], v[182:185], v[222:225], v[76:79]
	v_mfma_f32_16x16x32_bf16 v[68:71], v[190:193], v[222:225], v[68:71]
	s_barrier
	s_add_i32 s52, s52, s37
	v_lshl_add_u64 v[226:227], s[20:21], 0, v[134:135]
	s_mov_b32 m0, s52
	ds_read_b128 v[194:197], v153 offset:16384
	ds_read_b128 v[198:201], v153 offset:17408
	ds_read_b128 v[202:205], v153 offset:18432
	ds_read_b128 v[206:209], v153 offset:19456
	ds_read_b128 v[210:213], v153 offset:20480
	ds_read_b128 v[214:217], v153 offset:21504
	ds_read_b128 v[218:221], v153 offset:22528
	ds_read_b128 v[222:225], v153 offset:23552
	global_load_lds_dwordx4 v[226:227], off
	s_add_i32 m0, s52, 0x2000
	s_add_u32 s52, s20, 0x40000
	v_lshl_add_u64 v[238:239], s[20:21], 0, v[0:1]
	s_addc_u32 s53, s21, 0
	s_add_i32 s54, s54, s37
	global_load_lds_dwordx4 v[238:239], off
	v_lshl_add_u64 v[240:241], s[52:53], 0, v[134:135]
	s_mov_b32 m0, s54
	v_lshl_add_u64 v[242:243], s[22:23], 0, v[132:133]
	global_load_lds_dwordx4 v[240:241], off
	v_lshl_add_u64 v[240:241], s[52:53], 0, v[0:1]
	s_add_i32 m0, s54, 0x2000
	s_nop 0
	global_load_lds_dwordx4 v[240:241], off
	v_lshl_add_u64 v[240:241], s[22:23], 0, v[136:137]
	s_mov_b32 m0, s38
	s_nop 0
	global_load_lds_dwordx4 v[240:241], off
	s_mov_b32 m0, s39
	s_nop 0
	global_load_lds_dwordx4 v[242:243], off
	s_waitcnt vmcnt(8) lgkmcnt(0)
	s_barrier
; #define PG8_STAGE(bufoff, gbase, voff) do { _Pragma("unroll") for (int _i = 0; _i < 2; ++_i) \
;         __builtin_amdgcn_global_load_lds((const unsigned*)((const char*)(gbase) + (voff)[_i]), (PG8_LAS unsigned*)(lds + (bufoff) + ldsw + _i * 8192), 16, 0, 0); } while (0)
; #define PG8_LDA(dst, b, h) do { _Pragma("unroll") for (int m = 0; m < 4; ++m) _Pragma("unroll") for (int k = 0; k < 2; ++k) dst[m][k] = *(const PG8_LAS bf16x8*)(lds + PG8_SA(b, h) + aoff + m * 2048 + k * 1024); } while (0)
; #define PG8_LDB(dst, b, h) do { _Pragma("unroll") for (int n = 0; n < 2; ++n) _Pragma("unroll") for (int k = 0; k < 2; ++k) dst[n][k] = *(const PG8_LAS bf16x8*)(lds + PG8_SB(b, h) + boff + n * 2048 + k * 1024); } while (0)
; #define PG8_MMA(ai, bj, At, Bt) do { __builtin_amdgcn_s_setprio(1); _Pragma("unroll") for (int m = 0; m < 4; ++m) _Pragma("unroll") for (int n = 0; n < 2; ++n) _Pragma("unroll") for (int k = 0; k < 2; ++k) \
;         acc[ai][bj][m][n] = __builtin_amdgcn_mfma_f32_16x16x32_bf16(Bt[n][k], At[m][k], acc[ai][bj][m][n], 0, 0, 0); __builtin_amdgcn_s_setprio(0); } while (0)
; #define PG8_WAIT_V(n) asm volatile("s_waitcnt vmcnt(" #n ")" ::: "memory")
; #define PG8_WAIT_L(n) asm volatile("s_waitcnt lgkmcnt(" #n ")" ::: "memory")
; #define PG8_BAR __builtin_amdgcn_s_barrier()
; #define PG8_SCHED __builtin_amdgcn_sched_barrier(0)
; template <class Epi, class Sched, bool ALIGN_EPI = false, bool SP2 = false>
; __device__ __forceinline__ void gemm_phase(PG8_LAS unsigned char* lds, const Gemm g, const Sched& S, const Epi& E, const int tid) {
;     ...
;             PG8_WAIT_V(8); PG8_WAIT_L(0); PG8_BAR; PG8_MMA(1, 0, At, B0); PG8_MMA(1, 1, At, B1); PG8_BAR; PG8_SCHED;
;             PG8_LDB(B0, 1, 0); PG8_LDB(B1, 1, 1); PG8_SCHED; PG8_LDA(At, 1, 0); PG8_STAGE(PG8_SA(0, 1), a2 + hstep, voffA);
;             PG8_WAIT_V(8); PG8_WAIT_L(0); PG8_BAR; PG8_MMA(0, 0, At, B0); PG8_MMA(0, 1, At, B1); PG8_BAR; PG8_SCHED;
	v_mfma_f32_16x16x32_bf16 v[64:67], v[142:145], v[194:197], v[64:67]
	v_mfma_f32_16x16x32_bf16 v[56:59], v[170:173], v[194:197], v[56:59]
	v_mfma_f32_16x16x32_bf16 v[48:51], v[142:145], v[202:205], v[48:51]
	v_mfma_f32_16x16x32_bf16 v[40:43], v[170:173], v[202:205], v[40:43]
	v_mfma_f32_16x16x32_bf16 v[32:35], v[142:145], v[210:213], v[32:35]
	v_mfma_f32_16x16x32_bf16 v[24:27], v[170:173], v[210:213], v[24:27]
	v_mfma_f32_16x16x32_bf16 v[16:19], v[142:145], v[218:221], v[16:19]
	v_mfma_f32_16x16x32_bf16 v[8:11], v[170:173], v[218:221], v[8:11]
	v_mfma_f32_16x16x32_bf16 v[64:67], v[166:169], v[198:201], v[64:67]
	v_mfma_f32_16x16x32_bf16 v[56:59], v[174:177], v[198:201], v[56:59]
	v_mfma_f32_16x16x32_bf16 v[48:51], v[166:169], v[206:209], v[48:51]
	v_mfma_f32_16x16x32_bf16 v[40:43], v[174:177], v[206:209], v[40:43]
	v_mfma_f32_16x16x32_bf16 v[32:35], v[166:169], v[214:217], v[32:35]
	v_mfma_f32_16x16x32_bf16 v[24:27], v[174:177], v[214:217], v[24:27]
	v_mfma_f32_16x16x32_bf16 v[16:19], v[166:169], v[222:225], v[16:19]
	v_mfma_f32_16x16x32_bf16 v[8:11], v[174:177], v[222:225], v[8:11]
	v_mfma_f32_16x16x32_bf16 v[60:63], v[178:181], v[194:197], v[60:63]
	v_mfma_f32_16x16x32_bf16 v[52:55], v[186:189], v[194:197], v[52:55]
	v_mfma_f32_16x16x32_bf16 v[44:47], v[178:181], v[202:205], v[44:47]
	v_mfma_f32_16x16x32_bf16 v[36:39], v[186:189], v[202:205], v[36:39]
	v_mfma_f32_16x16x32_bf16 v[28:31], v[178:181], v[210:213], v[28:31]
	v_mfma_f32_16x16x32_bf16 v[20:23], v[186:189], v[210:213], v[20:23]
	v_mfma_f32_16x16x32_bf16 v[12:15], v[178:181], v[218:221], v[12:15]
	v_mfma_f32_16x16x32_bf16 v[4:7], v[186:189], v[218:221], v[4:7]
	v_mfma_f32_16x16x32_bf16 v[60:63], v[182:185], v[198:201], v[60:63]
	v_mfma_f32_16x16x32_bf16 v[52:55], v[190:193], v[198:201], v[52:55]
	v_mfma_f32_16x16x32_bf16 v[44:47], v[182:185], v[206:209], v[44:47]
	v_mfma_f32_16x16x32_bf16 v[36:39], v[190:193], v[206:209], v[36:39]
	v_mfma_f32_16x16x32_bf16 v[28:31], v[182:185], v[214:217], v[28:31]
	v_mfma_f32_16x16x32_bf16 v[20:23], v[190:193], v[214:217], v[20:23]
	v_mfma_f32_16x16x32_bf16 v[12:15], v[182:185], v[222:225], v[12:15]
	v_mfma_f32_16x16x32_bf16 v[4:7], v[190:193], v[222:225], v[4:7]
	s_barrier
	s_add_i32 s52, 0, 0x18000
	v_add_u32_e32 v148, s52, v146
	s_add_i32 s53, 0, 0x1c000
	ds_read_b128 v[142:145], v148
	ds_read_b128 v[166:169], v148 offset:1024
	ds_read_b128 v[170:173], v148 offset:2048
	ds_read_b128 v[174:177], v148 offset:3072
	v_add_u32_e32 v148, s53, v146
	ds_read_b128 v[178:181], v148
	ds_read_b128 v[182:185], v148 offset:1024
	ds_read_b128 v[186:189], v148 offset:2048
	ds_read_b128 v[190:193], v148 offset:3072
	s_add_u32 s22, s22, 0x40000
	s_addc_u32 s23, s23, 0
	s_mov_b32 m0, s40
	v_lshl_add_u64 v[244:245], s[22:23], 0, v[136:137]
	ds_read_b128 v[194:197], v153 offset:32768
	ds_read_b128 v[198:201], v153 offset:33792
	ds_read_b128 v[202:205], v153 offset:34816
	ds_read_b128 v[206:209], v153 offset:35840
	ds_read_b128 v[210:213], v153 offset:36864
	ds_read_b128 v[214:217], v153 offset:37888
	ds_read_b128 v[218:221], v153 offset:38912
	ds_read_b128 v[222:225], v153 offset:39936
	global_load_lds_dwordx4 v[244:245], off
	v_lshl_add_u64 v[244:245], s[22:23], 0, v[132:133]
	s_mov_b32 m0, s41
	s_nop 0
	global_load_lds_dwordx4 v[244:245], off
	s_waitcnt vmcnt(8) lgkmcnt(0)
	s_barrier
	v_mfma_f32_16x16x32_bf16 v[128:131], v[142:145], v[194:197], v[128:131]
	v_mfma_f32_16x16x32_bf16 v[120:123], v[170:173], v[194:197], v[120:123]
	v_mfma_f32_16x16x32_bf16 v[112:115], v[142:145], v[202:205], v[112:115]
	v_mfma_f32_16x16x32_bf16 v[104:107], v[170:173], v[202:205], v[104:107]
	v_mfma_f32_16x16x32_bf16 v[96:99], v[142:145], v[210:213], v[96:99]
	v_mfma_f32_16x16x32_bf16 v[88:91], v[170:173], v[210:213], v[88:91]
	v_mfma_f32_16x16x32_bf16 v[80:83], v[142:145], v[218:221], v[80:83]
	v_mfma_f32_16x16x32_bf16 v[72:75], v[170:173], v[218:221], v[72:75]
	v_mfma_f32_16x16x32_bf16 v[128:131], v[166:169], v[198:201], v[128:131]
	v_mfma_f32_16x16x32_bf16 v[120:123], v[174:177], v[198:201], v[120:123]
	v_mfma_f32_16x16x32_bf16 v[112:115], v[166:169], v[206:209], v[112:115]
	v_mfma_f32_16x16x32_bf16 v[104:107], v[174:177], v[206:209], v[104:107]
	v_mfma_f32_16x16x32_bf16 v[96:99], v[166:169], v[214:217], v[96:99]
	v_mfma_f32_16x16x32_bf16 v[88:91], v[174:177], v[214:217], v[88:91]
	v_mfma_f32_16x16x32_bf16 v[80:83], v[166:169], v[222:225], v[80:83]
	v_mfma_f32_16x16x32_bf16 v[72:75], v[174:177], v[222:225], v[72:75]
	v_mfma_f32_16x16x32_bf16 v[124:127], v[178:181], v[194:197], v[124:127]
	v_mfma_f32_16x16x32_bf16 v[116:119], v[186:189], v[194:197], v[116:119]
	v_mfma_f32_16x16x32_bf16 v[108:111], v[178:181], v[202:205], v[108:111]
	v_mfma_f32_16x16x32_bf16 v[100:103], v[186:189], v[202:205], v[100:103]
	v_mfma_f32_16x16x32_bf16 v[92:95], v[178:181], v[210:213], v[92:95]
	v_mfma_f32_16x16x32_bf16 v[84:87], v[186:189], v[210:213], v[84:87]
	v_mfma_f32_16x16x32_bf16 v[76:79], v[178:181], v[218:221], v[76:79]
	v_mfma_f32_16x16x32_bf16 v[68:71], v[186:189], v[218:221], v[68:71]
	v_mfma_f32_16x16x32_bf16 v[124:127], v[182:185], v[198:201], v[124:127]
	v_mfma_f32_16x16x32_bf16 v[116:119], v[190:193], v[198:201], v[116:119]
	v_mfma_f32_16x16x32_bf16 v[108:111], v[182:185], v[206:209], v[108:111]
	v_mfma_f32_16x16x32_bf16 v[100:103], v[190:193], v[206:209], v[100:103]
	v_mfma_f32_16x16x32_bf16 v[92:95], v[182:185], v[214:217], v[92:95]
	v_mfma_f32_16x16x32_bf16 v[84:87], v[190:193], v[214:217], v[84:87]
	v_mfma_f32_16x16x32_bf16 v[76:79], v[182:185], v[222:225], v[76:79]
	v_mfma_f32_16x16x32_bf16 v[68:71], v[190:193], v[222:225], v[68:71]
	s_barrier
; #define PG8_STAGE(bufoff, gbase, voff) do { _Pragma("unroll") for (int _i = 0; _i < 2; ++_i) \
;         __builtin_amdgcn_global_load_lds((const unsigned*)((const char*)(gbase) + (voff)[_i]), (PG8_LAS unsigned*)(lds + (bufoff) + ldsw + _i * 8192), 16, 0, 0); } while (0)
; #define PG8_LDA(dst, b, h) do { _Pragma("unroll") for (int m = 0; m < 4; ++m) _Pragma("unroll") for (int k = 0; k < 2; ++k) dst[m][k] = *(const PG8_LAS bf16x8*)(lds + PG8_SA(b, h) + aoff + m * 2048 + k * 1024); } while (0)
; #define PG8_MMA(ai, bj, At, Bt) do { __builtin_amdgcn_s_setprio(1); _Pragma("unroll") for (int m = 0; m < 4; ++m) _Pragma("unroll") for (int n = 0; n < 2; ++n) _Pragma("unroll") for (int k = 0; k < 2; ++k) \
;         acc[ai][bj][m][n] = __builtin_amdgcn_mfma_f32_16x16x32_bf16(Bt[n][k], At[m][k], acc[ai][bj][m][n], 0, 0, 0); __builtin_amdgcn_s_setprio(0); } while (0)
; #define PG8_WAIT_V(n) asm volatile("s_waitcnt vmcnt(" #n ")" ::: "memory")
; #define PG8_WAIT_L(n) asm volatile("s_waitcnt lgkmcnt(" #n ")" ::: "memory")
; #define PG8_BAR __builtin_amdgcn_s_barrier()
; #define PG8_SCHED __builtin_amdgcn_sched_barrier(0)
; template <class Epi, class Sched, bool ALIGN_EPI = false, bool SP2 = false>
; __device__ __forceinline__ void gemm_phase(PG8_LAS unsigned char* lds, const Gemm g, const Sched& S, const Epi& E, const int tid) {
;     ...
;             PG8_LDA(At, 1, 1); PG8_STAGE(PG8_SB(1, 0), b3, voffB); PG8_STAGE(PG8_SB(1, 1), b3 + hstep, voffB); PG8_STAGE(PG8_SA(1, 0), a3, voffA);
;             PG8_WAIT_V(8); PG8_WAIT_L(0); PG8_BAR; PG8_MMA(1, 0, At, B0); PG8_MMA(1, 1, At, B1); PG8_BAR; PG8_SCHED;
;     ...
;         if constexpr (ALIGN_EPI) { if (wr == 0) PG8_BAR; }
	s_add_i32 s22, s52, s37
	v_lshl_add_u64 v[226:227], v[226:227], 0, s[0:1]
	s_mov_b32 m0, s22
	ds_read_b128 v[194:197], v153 offset:49152
	ds_read_b128 v[198:201], v153 offset:50176
	ds_read_b128 v[202:205], v153 offset:51200
	ds_read_b128 v[206:209], v153 offset:52224
	ds_read_b128 v[210:213], v153 offset:53248
	ds_read_b128 v[214:217], v153 offset:54272
	ds_read_b128 v[218:221], v153 offset:55296
	ds_read_b128 v[222:225], v153 offset:56320
	global_load_lds_dwordx4 v[226:227], off
	s_add_i32 m0, s22, 0x2000
	s_add_u32 s20, s20, 0x40080
	v_lshl_add_u64 v[226:227], v[238:239], 0, s[0:1]
	s_addc_u32 s21, s21, 0
	s_add_i32 s22, s53, s37
	global_load_lds_dwordx4 v[226:227], off
	v_lshl_add_u64 v[226:227], s[20:21], 0, v[134:135]
	s_mov_b32 m0, s22
	s_nop 0
	global_load_lds_dwordx4 v[226:227], off
	v_lshl_add_u64 v[226:227], s[20:21], 0, v[0:1]
	s_add_i32 m0, s22, 0x2000
	s_nop 0
	global_load_lds_dwordx4 v[226:227], off
	v_lshl_add_u64 v[226:227], v[240:241], 0, s[0:1]
	s_mov_b32 m0, s42
	s_nop 0
	global_load_lds_dwordx4 v[226:227], off
	v_lshl_add_u64 v[226:227], v[242:243], 0, s[0:1]
	s_mov_b32 m0, s43
	s_nop 0
	global_load_lds_dwordx4 v[226:227], off
	s_waitcnt vmcnt(8) lgkmcnt(0)
	s_barrier
	v_mfma_f32_16x16x32_bf16 v[64:67], v[142:145], v[194:197], v[64:67]
	v_mfma_f32_16x16x32_bf16 v[56:59], v[170:173], v[194:197], v[56:59]
	v_mfma_f32_16x16x32_bf16 v[48:51], v[142:145], v[202:205], v[48:51]
	v_mfma_f32_16x16x32_bf16 v[40:43], v[170:173], v[202:205], v[40:43]
	v_mfma_f32_16x16x32_bf16 v[32:35], v[142:145], v[210:213], v[32:35]
	v_mfma_f32_16x16x32_bf16 v[24:27], v[170:173], v[210:213], v[24:27]
	v_mfma_f32_16x16x32_bf16 v[16:19], v[142:145], v[218:221], v[16:19]
	v_mfma_f32_16x16x32_bf16 v[8:11], v[170:173], v[218:221], v[8:11]
	v_mfma_f32_16x16x32_bf16 v[64:67], v[166:169], v[198:201], v[64:67]
	v_mfma_f32_16x16x32_bf16 v[56:59], v[174:177], v[198:201], v[56:59]
	v_mfma_f32_16x16x32_bf16 v[48:51], v[166:169], v[206:209], v[48:51]
	v_mfma_f32_16x16x32_bf16 v[40:43], v[174:177], v[206:209], v[40:43]
	v_mfma_f32_16x16x32_bf16 v[32:35], v[166:169], v[214:217], v[32:35]
	v_mfma_f32_16x16x32_bf16 v[24:27], v[174:177], v[214:217], v[24:27]
	v_mfma_f32_16x16x32_bf16 v[16:19], v[166:169], v[222:225], v[16:19]
	v_mfma_f32_16x16x32_bf16 v[8:11], v[174:177], v[222:225], v[8:11]
	v_mfma_f32_16x16x32_bf16 v[60:63], v[178:181], v[194:197], v[60:63]
	v_mfma_f32_16x16x32_bf16 v[52:55], v[186:189], v[194:197], v[52:55]
	v_mfma_f32_16x16x32_bf16 v[44:47], v[178:181], v[202:205], v[44:47]
	v_mfma_f32_16x16x32_bf16 v[36:39], v[186:189], v[202:205], v[36:39]
	v_mfma_f32_16x16x32_bf16 v[28:31], v[178:181], v[210:213], v[28:31]
	v_mfma_f32_16x16x32_bf16 v[20:23], v[186:189], v[210:213], v[20:23]
	v_mfma_f32_16x16x32_bf16 v[12:15], v[178:181], v[218:221], v[12:15]
	v_mfma_f32_16x16x32_bf16 v[4:7], v[186:189], v[218:221], v[4:7]
	v_mfma_f32_16x16x32_bf16 v[60:63], v[182:185], v[198:201], v[60:63]
	v_mfma_f32_16x16x32_bf16 v[52:55], v[190:193], v[198:201], v[52:55]
	v_mfma_f32_16x16x32_bf16 v[44:47], v[182:185], v[206:209], v[44:47]
	v_mfma_f32_16x16x32_bf16 v[36:39], v[190:193], v[206:209], v[36:39]
	v_mfma_f32_16x16x32_bf16 v[28:31], v[182:185], v[214:217], v[28:31]
	v_mfma_f32_16x16x32_bf16 v[20:23], v[190:193], v[214:217], v[20:23]
	v_mfma_f32_16x16x32_bf16 v[12:15], v[182:185], v[222:225], v[12:15]
	v_mfma_f32_16x16x32_bf16 v[4:7], v[190:193], v[222:225], v[4:7]
	s_barrier
	s_add_i32 s51, s51, 2
	s_add_u32 s18, s18, 0x100
	s_addc_u32 s19, s19, 0
	s_add_u32 s49, s49, 0x100
	s_addc_u32 s50, s50, 0
	s_cmp_gt_u32 s51, 13
	s_cbranch_scc0 .LBB0_522
	s_and_b64 vcc, exec, s[8:9]
	s_cbranch_vccz .LBB0_525
	s_barrier

; #define PG8_STAGE(bufoff, gbase, voff) do { _Pragma("unroll") for (int _i = 0; _i < 2; ++_i) \
;         __builtin_amdgcn_global_load_lds((const unsigned*)((const char*)(gbase) + (voff)[_i]), (PG8_LAS unsigned*)(lds + (bufoff) + ldsw + _i * 8192), 16, 0, 0); } while (0)
; #define PG8_LDA(dst, b, h) do { _Pragma("unroll") for (int m = 0; m < 4; ++m) _Pragma("unroll") for (int k = 0; k < 2; ++k) dst[m][k] = *(const PG8_LAS bf16x8*)(lds + PG8_SA(b, h) + aoff + m * 2048 + k * 1024); } while (0)
; #define PG8_LDB(dst, b, h) do { _Pragma("unroll") for (int n = 0; n < 2; ++n) _Pragma("unroll") for (int k = 0; k < 2; ++k) dst[n][k] = *(const PG8_LAS bf16x8*)(lds + PG8_SB(b, h) + boff + n * 2048 + k * 1024); } while (0)
; #define PG8_MMA(ai, bj, At, Bt) do { __builtin_amdgcn_s_setprio(1); _Pragma("unroll") for (int m = 0; m < 4; ++m) _Pragma("unroll") for (int n = 0; n < 2; ++n) _Pragma("unroll") for (int k = 0; k < 2; ++k) \
;         acc[ai][bj][m][n] = __builtin_amdgcn_mfma_f32_16x16x32_bf16(Bt[n][k], At[m][k], acc[ai][bj][m][n], 0, 0, 0); __builtin_amdgcn_s_setprio(0); } while (0)
; #define PG8_WAIT_V(n) asm volatile("s_waitcnt vmcnt(" #n ")" ::: "memory")
; #define PG8_WAIT_L(n) asm volatile("s_waitcnt lgkmcnt(" #n ")" ::: "memory")
; #define PG8_BAR __builtin_amdgcn_s_barrier()
; #define PG8_SCHED __builtin_amdgcn_sched_barrier(0)
; template <class Epi, class Sched, bool ALIGN_EPI = false, bool SP2 = false>
; __device__ __forceinline__ void gemm_phase(PG8_LAS unsigned char* lds, const Gemm g, const Sched& S, const Epi& E, const int tid) {
;     ...
;             const bool last = (t == nt - 2);
;             const char* a1 = cA + (size_t)(t + 1) * kstep;
;             const char* a2 = last ? nA : cA + (size_t)(t + 2) * kstep; const char* b2 = last ? nB : cB + (size_t)(t + 2) * kstep;
;             const char* a3 = a2 + kstep; const char* b3 = b2 + kstep;
;             if (last && has_next) S.a_ready(nxt);
;             if constexpr (SP2) {
;             PG8_LDB(B0, 0, 0); PG8_LDB(B1, 0, 1); PG8_SCHED; PG8_LDA(At, 0, 0); PG8_STAGE(PG8_SA(1, 1), a1 + hstep, voffA);
;             PG8_WAIT_V(8); PG8_WAIT_L(0); PG8_BAR; PG8_MMA(0, 0, At, B0); PG8_MMA(0, 1, At, B1); PG8_BAR; PG8_SCHED;
;             PG8_LDA(At, 0, 1); PG8_STAGE(PG8_SB(0, 0), b2, voffB); PG8_STAGE(PG8_SB(0, 1), b2 + hstep, voffB); PG8_STAGE(PG8_SA(0, 0), a2, voffA);
.LBB0_842:
	s_add_u32 s24, s22, 0xfffc0080
	s_addc_u32 s25, s23, -1
	s_add_i32 s50, 0, 0x10000
	s_cmp_eq_u32 s49, 12
	s_cselect_b32 s27, s13, s25
	s_cselect_b32 s26, s19, s24
	v_add_u32_e32 v148, s50, v146
	s_cselect_b32 s25, s11, s48
	s_cselect_b32 s24, s46, s47
	s_add_i32 s52, 0, 0x14000
	ds_read_b128 v[142:145], v148
	ds_read_b128 v[166:169], v148 offset:1024
	ds_read_b128 v[170:173], v148 offset:2048
	ds_read_b128 v[174:177], v148 offset:3072
	v_add_u32_e32 v148, s52, v146
	ds_read_b128 v[178:181], v148
	ds_read_b128 v[182:185], v148 offset:1024
	ds_read_b128 v[186:189], v148 offset:2048
	ds_read_b128 v[190:193], v148 offset:3072
	v_lshl_add_u64 v[226:227], s[22:23], 0, v[138:139]
	s_add_i32 m0, s21, 0xc000
	ds_read_b128 v[194:197], v153
	ds_read_b128 v[198:201], v153 offset:1024
	ds_read_b128 v[202:205], v153 offset:2048
	ds_read_b128 v[206:209], v153 offset:3072
	ds_read_b128 v[210:213], v153 offset:4096
	ds_read_b128 v[214:217], v153 offset:5120
	ds_read_b128 v[218:221], v153 offset:6144
	ds_read_b128 v[222:225], v153 offset:7168
	global_load_lds_dwordx4 v[226:227], off
	v_lshl_add_u64 v[226:227], s[22:23], 0, v[140:141]
	s_add_i32 m0, s21, 0xe000
	s_nop 0
	global_load_lds_dwordx4 v[226:227], off
	s_waitcnt vmcnt(8) lgkmcnt(0)
	s_barrier
	v_mfma_f32_16x16x32_bf16 v[128:131], v[142:145], v[194:197], v[128:131]
	v_mfma_f32_16x16x32_bf16 v[124:127], v[170:173], v[194:197], v[124:127]
	v_mfma_f32_16x16x32_bf16 v[112:115], v[142:145], v[202:205], v[112:115]
	v_mfma_f32_16x16x32_bf16 v[108:111], v[170:173], v[202:205], v[108:111]
	v_mfma_f32_16x16x32_bf16 v[96:99], v[142:145], v[210:213], v[96:99]
	v_mfma_f32_16x16x32_bf16 v[92:95], v[170:173], v[210:213], v[92:95]
	v_mfma_f32_16x16x32_bf16 v[80:83], v[142:145], v[218:221], v[80:83]
	v_mfma_f32_16x16x32_bf16 v[76:79], v[170:173], v[218:221], v[76:79]
	v_mfma_f32_16x16x32_bf16 v[128:131], v[166:169], v[198:201], v[128:131]
	v_mfma_f32_16x16x32_bf16 v[124:127], v[174:177], v[198:201], v[124:127]
	v_mfma_f32_16x16x32_bf16 v[112:115], v[166:169], v[206:209], v[112:115]
	v_mfma_f32_16x16x32_bf16 v[108:111], v[174:177], v[206:209], v[108:111]
	v_mfma_f32_16x16x32_bf16 v[96:99], v[166:169], v[214:217], v[96:99]
	v_mfma_f32_16x16x32_bf16 v[92:95], v[174:177], v[214:217], v[92:95]
	v_mfma_f32_16x16x32_bf16 v[80:83], v[166:169], v[222:225], v[80:83]
	v_mfma_f32_16x16x32_bf16 v[76:79], v[174:177], v[222:225], v[76:79]
	v_mfma_f32_16x16x32_bf16 v[120:123], v[178:181], v[194:197], v[120:123]
	v_mfma_f32_16x16x32_bf16 v[116:119], v[186:189], v[194:197], v[116:119]
	v_mfma_f32_16x16x32_bf16 v[104:107], v[178:181], v[202:205], v[104:107]
	v_mfma_f32_16x16x32_bf16 v[100:103], v[186:189], v[202:205], v[100:103]
	v_mfma_f32_16x16x32_bf16 v[88:91], v[178:181], v[210:213], v[88:91]
	v_mfma_f32_16x16x32_bf16 v[84:87], v[186:189], v[210:213], v[84:87]
	v_mfma_f32_16x16x32_bf16 v[72:75], v[178:181], v[218:221], v[72:75]
	v_mfma_f32_16x16x32_bf16 v[68:71], v[186:189], v[218:221], v[68:71]
	v_mfma_f32_16x16x32_bf16 v[120:123], v[182:185], v[198:201], v[120:123]
	v_mfma_f32_16x16x32_bf16 v[116:119], v[190:193], v[198:201], v[116:119]
	v_mfma_f32_16x16x32_bf16 v[104:107], v[182:185], v[206:209], v[104:107]
	v_mfma_f32_16x16x32_bf16 v[100:103], v[190:193], v[206:209], v[100:103]
	v_mfma_f32_16x16x32_bf16 v[88:91], v[182:185], v[214:217], v[88:91]
	v_mfma_f32_16x16x32_bf16 v[84:87], v[190:193], v[214:217], v[84:87]
	v_mfma_f32_16x16x32_bf16 v[72:75], v[182:185], v[222:225], v[72:75]
	v_mfma_f32_16x16x32_bf16 v[68:71], v[190:193], v[222:225], v[68:71]
	s_barrier
	s_add_i32 s50, s50, s37
	v_lshl_add_u64 v[226:227], s[24:25], 0, v[132:133]
	s_mov_b32 m0, s50
	ds_read_b128 v[194:197], v153 offset:16384
	ds_read_b128 v[198:201], v153 offset:17408
	ds_read_b128 v[202:205], v153 offset:18432
	ds_read_b128 v[206:209], v153 offset:19456
	ds_read_b128 v[210:213], v153 offset:20480
	ds_read_b128 v[214:217], v153 offset:21504
	ds_read_b128 v[218:221], v153 offset:22528
	ds_read_b128 v[222:225], v153 offset:23552
	global_load_lds_dwordx4 v[226:227], off
	s_add_i32 m0, s50, 0x2000
	s_add_u32 s50, s24, 0x40000
	v_lshl_add_u64 v[238:239], s[24:25], 0, v[136:137]
	s_addc_u32 s51, s25, 0
	s_add_i32 s52, s52, s37
	global_load_lds_dwordx4 v[238:239], off
	v_lshl_add_u64 v[240:241], s[50:51], 0, v[132:133]
	s_mov_b32 m0, s52
	v_lshl_add_u64 v[242:243], s[26:27], 0, v[134:135]
	global_load_lds_dwordx4 v[240:241], off
	v_lshl_add_u64 v[240:241], s[50:51], 0, v[136:137]
	s_add_i32 m0, s52, 0x2000
	s_nop 0
	global_load_lds_dwordx4 v[240:241], off
	v_lshl_add_u64 v[240:241], s[26:27], 0, v[0:1]
	s_mov_b32 m0, s21
	s_nop 0
	global_load_lds_dwordx4 v[240:241], off
	s_mov_b32 m0, s40
	s_nop 0
	global_load_lds_dwordx4 v[242:243], off
	s_waitcnt vmcnt(8) lgkmcnt(0)
	s_barrier
; #define PG8_STAGE(bufoff, gbase, voff) do { _Pragma("unroll") for (int _i = 0; _i < 2; ++_i) \
;         __builtin_amdgcn_global_load_lds((const unsigned*)((const char*)(gbase) + (voff)[_i]), (PG8_LAS unsigned*)(lds + (bufoff) + ldsw + _i * 8192), 16, 0, 0); } while (0)
; #define PG8_LDA(dst, b, h) do { _Pragma("unroll") for (int m = 0; m < 4; ++m) _Pragma("unroll") for (int k = 0; k < 2; ++k) dst[m][k] = *(const PG8_LAS bf16x8*)(lds + PG8_SA(b, h) + aoff + m * 2048 + k * 1024); } while (0)
; #define PG8_LDB(dst, b, h) do { _Pragma("unroll") for (int n = 0; n < 2; ++n) _Pragma("unroll") for (int k = 0; k < 2; ++k) dst[n][k] = *(const PG8_LAS bf16x8*)(lds + PG8_SB(b, h) + boff + n * 2048 + k * 1024); } while (0)
; #define PG8_MMA(ai, bj, At, Bt) do { __builtin_amdgcn_s_setprio(1); _Pragma("unroll") for (int m = 0; m < 4; ++m) _Pragma("unroll") for (int n = 0; n < 2; ++n) _Pragma("unroll") for (int k = 0; k < 2; ++k) \
;         acc[ai][bj][m][n] = __builtin_amdgcn_mfma_f32_16x16x32_bf16(Bt[n][k], At[m][k], acc[ai][bj][m][n], 0, 0, 0); __builtin_amdgcn_s_setprio(0); } while (0)
; #define PG8_WAIT_V(n) asm volatile("s_waitcnt vmcnt(" #n ")" ::: "memory")
; #define PG8_WAIT_L(n) asm volatile("s_waitcnt lgkmcnt(" #n ")" ::: "memory")
; #define PG8_BAR __builtin_amdgcn_s_barrier()
; #define PG8_SCHED __builtin_amdgcn_sched_barrier(0)
; template <class Epi, class Sched, bool ALIGN_EPI = false, bool SP2 = false>
; __device__ __forceinline__ void gemm_phase(PG8_LAS unsigned char* lds, const Gemm g, const Sched& S, const Epi& E, const int tid) {
;     ...
;             PG8_WAIT_V(8); PG8_WAIT_L(0); PG8_BAR; PG8_MMA(1, 0, At, B0); PG8_MMA(1, 1, At, B1); PG8_BAR; PG8_SCHED;
;             PG8_LDB(B0, 1, 0); PG8_LDB(B1, 1, 1); PG8_SCHED; PG8_LDA(At, 1, 0); PG8_STAGE(PG8_SA(0, 1), a2 + hstep, voffA);
;             PG8_WAIT_V(8); PG8_WAIT_L(0); PG8_BAR; PG8_MMA(0, 0, At, B0); PG8_MMA(0, 1, At, B1); PG8_BAR; PG8_SCHED;
	v_mfma_f32_16x16x32_bf16 v[64:67], v[142:145], v[194:197], v[64:67]
	v_mfma_f32_16x16x32_bf16 v[60:63], v[170:173], v[194:197], v[60:63]
	v_mfma_f32_16x16x32_bf16 v[48:51], v[142:145], v[202:205], v[48:51]
	v_mfma_f32_16x16x32_bf16 v[44:47], v[170:173], v[202:205], v[44:47]
	v_mfma_f32_16x16x32_bf16 v[32:35], v[142:145], v[210:213], v[32:35]
	v_mfma_f32_16x16x32_bf16 v[28:31], v[170:173], v[210:213], v[28:31]
	v_mfma_f32_16x16x32_bf16 v[16:19], v[142:145], v[218:221], v[16:19]
	v_mfma_f32_16x16x32_bf16 v[12:15], v[170:173], v[218:221], v[12:15]
	v_mfma_f32_16x16x32_bf16 v[64:67], v[166:169], v[198:201], v[64:67]
	v_mfma_f32_16x16x32_bf16 v[60:63], v[174:177], v[198:201], v[60:63]
	v_mfma_f32_16x16x32_bf16 v[48:51], v[166:169], v[206:209], v[48:51]
	v_mfma_f32_16x16x32_bf16 v[44:47], v[174:177], v[206:209], v[44:47]
	v_mfma_f32_16x16x32_bf16 v[32:35], v[166:169], v[214:217], v[32:35]
	v_mfma_f32_16x16x32_bf16 v[28:31], v[174:177], v[214:217], v[28:31]
	v_mfma_f32_16x16x32_bf16 v[16:19], v[166:169], v[222:225], v[16:19]
	v_mfma_f32_16x16x32_bf16 v[12:15], v[174:177], v[222:225], v[12:15]
	v_mfma_f32_16x16x32_bf16 v[56:59], v[178:181], v[194:197], v[56:59]
	v_mfma_f32_16x16x32_bf16 v[52:55], v[186:189], v[194:197], v[52:55]
	v_mfma_f32_16x16x32_bf16 v[40:43], v[178:181], v[202:205], v[40:43]
	v_mfma_f32_16x16x32_bf16 v[36:39], v[186:189], v[202:205], v[36:39]
	v_mfma_f32_16x16x32_bf16 v[24:27], v[178:181], v[210:213], v[24:27]
	v_mfma_f32_16x16x32_bf16 v[20:23], v[186:189], v[210:213], v[20:23]
	v_mfma_f32_16x16x32_bf16 v[8:11], v[178:181], v[218:221], v[8:11]
	v_mfma_f32_16x16x32_bf16 v[4:7], v[186:189], v[218:221], v[4:7]
	v_mfma_f32_16x16x32_bf16 v[56:59], v[182:185], v[198:201], v[56:59]
	v_mfma_f32_16x16x32_bf16 v[52:55], v[190:193], v[198:201], v[52:55]
	v_mfma_f32_16x16x32_bf16 v[40:43], v[182:185], v[206:209], v[40:43]
	v_mfma_f32_16x16x32_bf16 v[36:39], v[190:193], v[206:209], v[36:39]
	v_mfma_f32_16x16x32_bf16 v[24:27], v[182:185], v[214:217], v[24:27]
	v_mfma_f32_16x16x32_bf16 v[20:23], v[190:193], v[214:217], v[20:23]
	v_mfma_f32_16x16x32_bf16 v[8:11], v[182:185], v[222:225], v[8:11]
	v_mfma_f32_16x16x32_bf16 v[4:7], v[190:193], v[222:225], v[4:7]
	s_barrier
	s_add_i32 s50, 0, 0x18000
	v_add_u32_e32 v148, s50, v146
	s_add_i32 s51, 0, 0x1c000
	ds_read_b128 v[142:145], v148
	ds_read_b128 v[166:169], v148 offset:1024
	ds_read_b128 v[170:173], v148 offset:2048
	ds_read_b128 v[174:177], v148 offset:3072
	v_add_u32_e32 v148, s51, v146
	ds_read_b128 v[178:181], v148
	ds_read_b128 v[182:185], v148 offset:1024
	ds_read_b128 v[186:189], v148 offset:2048
	ds_read_b128 v[190:193], v148 offset:3072
	s_add_u32 s26, s26, 0x40000
	s_addc_u32 s27, s27, 0
	s_mov_b32 m0, s41
	v_lshl_add_u64 v[244:245], s[26:27], 0, v[0:1]
	ds_read_b128 v[194:197], v153 offset:32768
	ds_read_b128 v[198:201], v153 offset:33792
	ds_read_b128 v[202:205], v153 offset:34816
	ds_read_b128 v[206:209], v153 offset:35840
	ds_read_b128 v[210:213], v153 offset:36864
	ds_read_b128 v[214:217], v153 offset:37888
	ds_read_b128 v[218:221], v153 offset:38912
	ds_read_b128 v[222:225], v153 offset:39936
	global_load_lds_dwordx4 v[244:245], off
	v_lshl_add_u64 v[244:245], s[26:27], 0, v[134:135]
	s_mov_b32 m0, s42
	s_nop 0
	global_load_lds_dwordx4 v[244:245], off
	s_waitcnt vmcnt(8) lgkmcnt(0)
	s_barrier
	v_mfma_f32_16x16x32_bf16 v[128:131], v[142:145], v[194:197], v[128:131]
	v_mfma_f32_16x16x32_bf16 v[124:127], v[170:173], v[194:197], v[124:127]
	v_mfma_f32_16x16x32_bf16 v[112:115], v[142:145], v[202:205], v[112:115]
	v_mfma_f32_16x16x32_bf16 v[108:111], v[170:173], v[202:205], v[108:111]
	v_mfma_f32_16x16x32_bf16 v[96:99], v[142:145], v[210:213], v[96:99]
	v_mfma_f32_16x16x32_bf16 v[92:95], v[170:173], v[210:213], v[92:95]
	v_mfma_f32_16x16x32_bf16 v[80:83], v[142:145], v[218:221], v[80:83]
	v_mfma_f32_16x16x32_bf16 v[76:79], v[170:173], v[218:221], v[76:79]
	v_mfma_f32_16x16x32_bf16 v[128:131], v[166:169], v[198:201], v[128:131]
	v_mfma_f32_16x16x32_bf16 v[124:127], v[174:177], v[198:201], v[124:127]
	v_mfma_f32_16x16x32_bf16 v[112:115], v[166:169], v[206:209], v[112:115]
	v_mfma_f32_16x16x32_bf16 v[108:111], v[174:177], v[206:209], v[108:111]
	v_mfma_f32_16x16x32_bf16 v[96:99], v[166:169], v[214:217], v[96:99]
	v_mfma_f32_16x16x32_bf16 v[92:95], v[174:177], v[214:217], v[92:95]
	v_mfma_f32_16x16x32_bf16 v[80:83], v[166:169], v[222:225], v[80:83]
	v_mfma_f32_16x16x32_bf16 v[76:79], v[174:177], v[222:225], v[76:79]
	v_mfma_f32_16x16x32_bf16 v[120:123], v[178:181], v[194:197], v[120:123]
	v_mfma_f32_16x16x32_bf16 v[116:119], v[186:189], v[194:197], v[116:119]
	v_mfma_f32_16x16x32_bf16 v[104:107], v[178:181], v[202:205], v[104:107]
	v_mfma_f32_16x16x32_bf16 v[100:103], v[186:189], v[202:205], v[100:103]
	v_mfma_f32_16x16x32_bf16 v[88:91], v[178:181], v[210:213], v[88:91]
	v_mfma_f32_16x16x32_bf16 v[84:87], v[186:189], v[210:213], v[84:87]
	v_mfma_f32_16x16x32_bf16 v[72:75], v[178:181], v[218:221], v[72:75]
	v_mfma_f32_16x16x32_bf16 v[68:71], v[186:189], v[218:221], v[68:71]
	v_mfma_f32_16x16x32_bf16 v[120:123], v[182:185], v[198:201], v[120:123]
	v_mfma_f32_16x16x32_bf16 v[116:119], v[190:193], v[198:201], v[116:119]
	v_mfma_f32_16x16x32_bf16 v[104:107], v[182:185], v[206:209], v[104:107]
	v_mfma_f32_16x16x32_bf16 v[100:103], v[190:193], v[206:209], v[100:103]
	v_mfma_f32_16x16x32_bf16 v[88:91], v[182:185], v[214:217], v[88:91]
	v_mfma_f32_16x16x32_bf16 v[84:87], v[190:193], v[214:217], v[84:87]
	v_mfma_f32_16x16x32_bf16 v[72:75], v[182:185], v[222:225], v[72:75]
	v_mfma_f32_16x16x32_bf16 v[68:71], v[190:193], v[222:225], v[68:71]
	s_barrier
; #define PG8_STAGE(bufoff, gbase, voff) do { _Pragma("unroll") for (int _i = 0; _i < 2; ++_i) \
;         __builtin_amdgcn_global_load_lds((const unsigned*)((const char*)(gbase) + (voff)[_i]), (PG8_LAS unsigned*)(lds + (bufoff) + ldsw + _i * 8192), 16, 0, 0); } while (0)
; #define PG8_LDA(dst, b, h) do { _Pragma("unroll") for (int m = 0; m < 4; ++m) _Pragma("unroll") for (int k = 0; k < 2; ++k) dst[m][k] = *(const PG8_LAS bf16x8*)(lds + PG8_SA(b, h) + aoff + m * 2048 + k * 1024); } while (0)
; #define PG8_MMA(ai, bj, At, Bt) do { __builtin_amdgcn_s_setprio(1); _Pragma("unroll") for (int m = 0; m < 4; ++m) _Pragma("unroll") for (int n = 0; n < 2; ++n) _Pragma("unroll") for (int k = 0; k < 2; ++k) \
;         acc[ai][bj][m][n] = __builtin_amdgcn_mfma_f32_16x16x32_bf16(Bt[n][k], At[m][k], acc[ai][bj][m][n], 0, 0, 0); __builtin_amdgcn_s_setprio(0); } while (0)
; #define PG8_WAIT_V(n) asm volatile("s_waitcnt vmcnt(" #n ")" ::: "memory")
; #define PG8_WAIT_L(n) asm volatile("s_waitcnt lgkmcnt(" #n ")" ::: "memory")
; #define PG8_BAR __builtin_amdgcn_s_barrier()
; #define PG8_SCHED __builtin_amdgcn_sched_barrier(0)
; template <class Epi, class Sched, bool ALIGN_EPI = false, bool SP2 = false>
; __device__ __forceinline__ void gemm_phase(PG8_LAS unsigned char* lds, const Gemm g, const Sched& S, const Epi& E, const int tid) {
;     ...
;             PG8_LDA(At, 1, 1); PG8_STAGE(PG8_SB(1, 0), b3, voffB); PG8_STAGE(PG8_SB(1, 1), b3 + hstep, voffB); PG8_STAGE(PG8_SA(1, 0), a3, voffA);
;             PG8_WAIT_V(8); PG8_WAIT_L(0); PG8_BAR; PG8_MMA(1, 0, At, B0); PG8_MMA(1, 1, At, B1); PG8_BAR; PG8_SCHED;
;     ...
;         if constexpr (ALIGN_EPI) { if (wr == 0) PG8_BAR; }
	s_add_i32 s26, s50, s37
	v_lshl_add_u64 v[226:227], v[226:227], 0, s[0:1]
	s_mov_b32 m0, s26
	ds_read_b128 v[194:197], v153 offset:49152
	ds_read_b128 v[198:201], v153 offset:50176
	ds_read_b128 v[202:205], v153 offset:51200
	ds_read_b128 v[206:209], v153 offset:52224
	ds_read_b128 v[210:213], v153 offset:53248
	ds_read_b128 v[214:217], v153 offset:54272
	ds_read_b128 v[218:221], v153 offset:55296
	ds_read_b128 v[222:225], v153 offset:56320
	global_load_lds_dwordx4 v[226:227], off
	s_add_i32 m0, s26, 0x2000
	s_add_u32 s24, s24, 0x40080
	v_lshl_add_u64 v[226:227], v[238:239], 0, s[0:1]
	s_addc_u32 s25, s25, 0
	s_add_i32 s26, s51, s37
	global_load_lds_dwordx4 v[226:227], off
	v_lshl_add_u64 v[226:227], s[24:25], 0, v[132:133]
	s_mov_b32 m0, s26
	s_nop 0
	global_load_lds_dwordx4 v[226:227], off
	v_lshl_add_u64 v[226:227], s[24:25], 0, v[136:137]
	s_add_i32 m0, s26, 0x2000
	s_nop 0
	global_load_lds_dwordx4 v[226:227], off
	v_lshl_add_u64 v[226:227], v[240:241], 0, s[0:1]
	s_mov_b32 m0, s43
	s_nop 0
	global_load_lds_dwordx4 v[226:227], off
	v_lshl_add_u64 v[226:227], v[242:243], 0, s[0:1]
	s_mov_b32 m0, s44
	s_nop 0
	global_load_lds_dwordx4 v[226:227], off
	s_waitcnt vmcnt(8) lgkmcnt(0)
	s_barrier
	v_mfma_f32_16x16x32_bf16 v[64:67], v[142:145], v[194:197], v[64:67]
	v_mfma_f32_16x16x32_bf16 v[60:63], v[170:173], v[194:197], v[60:63]
	v_mfma_f32_16x16x32_bf16 v[48:51], v[142:145], v[202:205], v[48:51]
	v_mfma_f32_16x16x32_bf16 v[44:47], v[170:173], v[202:205], v[44:47]
	v_mfma_f32_16x16x32_bf16 v[32:35], v[142:145], v[210:213], v[32:35]
	v_mfma_f32_16x16x32_bf16 v[28:31], v[170:173], v[210:213], v[28:31]
	v_mfma_f32_16x16x32_bf16 v[16:19], v[142:145], v[218:221], v[16:19]
	v_mfma_f32_16x16x32_bf16 v[12:15], v[170:173], v[218:221], v[12:15]
	v_mfma_f32_16x16x32_bf16 v[64:67], v[166:169], v[198:201], v[64:67]
	v_mfma_f32_16x16x32_bf16 v[60:63], v[174:177], v[198:201], v[60:63]
	v_mfma_f32_16x16x32_bf16 v[48:51], v[166:169], v[206:209], v[48:51]
	v_mfma_f32_16x16x32_bf16 v[44:47], v[174:177], v[206:209], v[44:47]
	v_mfma_f32_16x16x32_bf16 v[32:35], v[166:169], v[214:217], v[32:35]
	v_mfma_f32_16x16x32_bf16 v[28:31], v[174:177], v[214:217], v[28:31]
	v_mfma_f32_16x16x32_bf16 v[16:19], v[166:169], v[222:225], v[16:19]
	v_mfma_f32_16x16x32_bf16 v[12:15], v[174:177], v[222:225], v[12:15]
	v_mfma_f32_16x16x32_bf16 v[56:59], v[178:181], v[194:197], v[56:59]
	v_mfma_f32_16x16x32_bf16 v[52:55], v[186:189], v[194:197], v[52:55]
	v_mfma_f32_16x16x32_bf16 v[40:43], v[178:181], v[202:205], v[40:43]
	v_mfma_f32_16x16x32_bf16 v[36:39], v[186:189], v[202:205], v[36:39]
	v_mfma_f32_16x16x32_bf16 v[24:27], v[178:181], v[210:213], v[24:27]
	v_mfma_f32_16x16x32_bf16 v[20:23], v[186:189], v[210:213], v[20:23]
	v_mfma_f32_16x16x32_bf16 v[8:11], v[178:181], v[218:221], v[8:11]
	v_mfma_f32_16x16x32_bf16 v[4:7], v[186:189], v[218:221], v[4:7]
	v_mfma_f32_16x16x32_bf16 v[56:59], v[182:185], v[198:201], v[56:59]
	v_mfma_f32_16x16x32_bf16 v[52:55], v[190:193], v[198:201], v[52:55]
	v_mfma_f32_16x16x32_bf16 v[40:43], v[182:185], v[206:209], v[40:43]
	v_mfma_f32_16x16x32_bf16 v[36:39], v[190:193], v[206:209], v[36:39]
	v_mfma_f32_16x16x32_bf16 v[24:27], v[182:185], v[214:217], v[24:27]
	v_mfma_f32_16x16x32_bf16 v[20:23], v[190:193], v[214:217], v[20:23]
	v_mfma_f32_16x16x32_bf16 v[8:11], v[182:185], v[222:225], v[8:11]
	v_mfma_f32_16x16x32_bf16 v[4:7], v[190:193], v[222:225], v[4:7]
	s_barrier
	s_add_i32 s49, s49, 2
	s_add_u32 s22, s22, 0x100
	s_addc_u32 s23, s23, 0
	s_add_u32 s47, s47, 0x100
	s_addc_u32 s48, s48, 0
	s_cmp_gt_u32 s49, 13
	s_cbranch_scc0 .LBB0_842
	s_and_b64 vcc, exec, s[8:9]
	s_cbranch_vccz .LBB0_845
	s_barrier
